# GEMM K-loops (P1, P3b, P5, P6, P7): first K-iteration of every unit peeled with C=0 on the first MFMA of each accumulator; the 128 accumulator-zeroing v_mov per unit removed
# speedup vs baseline: 1.0037x; 1.0018x over previous
.LBB0_131:
	s_ashr_i32 s37, s36, 31
	s_lshl_b64 s[38:39], s[36:37], 19
	s_add_u32 s50, s10, s38
	s_addc_u32 s51, s11, s39
	s_and_b64 s[38:39], s[4:5], exec
	s_cselect_b32 s37, s51, s65
	s_cselect_b32 s38, s50, s64
	s_ashr_i32 s35, s34, 31
	s_lshl_b64 s[52:53], s[34:35], 19
	s_add_u32 s52, s80, s52
	s_addc_u32 s53, s81, s53
	s_and_b64 s[54:55], s[4:5], exec
	s_cselect_b32 s35, s53, s67
	s_cselect_b32 s39, s52, s66
	s_add_u32 s95, s66, 0x100
	s_addc_u32 s96, s67, 0
	s_mov_b32 s97, -2
	ds_read_b128 v[140:143], v129
	ds_read_b128 v[144:147], v129 offset:1024
	ds_read_b128 v[186:189], v129 offset:2048
	ds_read_b128 v[190:193], v129 offset:3072
	ds_read_b128 v[194:197], v164
	ds_read_b128 v[198:201], v164 offset:1024
	ds_read_b128 v[202:205], v164 offset:2048
	ds_read_b128 v[206:209], v164 offset:3072
	s_add_u32 s54, s64, 0x100
	s_addc_u32 s55, s65, 0
	s_cmp_eq_u32 s97, 12
	s_cselect_b32 s70, s38, s54
	s_cselect_b32 s71, s37, s55
	s_cselect_b32 s68, s39, s95
	s_cselect_b32 s69, s35, s96
	s_add_u32 s66, s70, 0x80
	s_addc_u32 s67, s71, 0
	ds_read_b128 v[210:213], v166
	ds_read_b128 v[214:217], v166 offset:1024
	ds_read_b128 v[218:221], v166 offset:2048
	ds_read_b128 v[222:225], v166 offset:3072
	ds_read_b128 v[226:229], v166 offset:4096
	ds_read_b128 v[230:233], v166 offset:5120
	ds_read_b128 v[234:237], v166 offset:6144
	ds_read_b128 v[238:241], v166 offset:7168
	s_add_u32 s64, s64, 0x40080
	v_readfirstlane_b32 vcc_lo, v167
	s_addc_u32 s65, s65, 0
	s_mov_b32 vcc_hi, m0
	s_mov_b32 m0, vcc_lo
	s_nop 0
	global_load_lds_dwordx4 v151, s[64:65]
	s_mov_b32 m0, vcc_hi
	v_readfirstlane_b32 vcc_lo, v168
	s_add_i32 vcc_lo, vcc_lo, 0
	s_add_i32 vcc_lo, vcc_lo, 0xe000
	s_mov_b32 vcc_hi, m0
	s_mov_b32 m0, vcc_lo
	s_nop 0
	global_load_lds_dwordx4 v153, s[64:65]
	s_mov_b32 m0, vcc_hi
	s_waitcnt vmcnt(8)
	s_waitcnt lgkmcnt(0)
	s_barrier
	s_setprio 1
	s_waitcnt lgkmcnt(7)
	v_mfma_f32_16x16x32_bf16 v[124:127], v[140:143], v[210:213], 0
	v_mfma_f32_16x16x32_bf16 v[120:123], v[186:189], v[210:213], 0
	s_waitcnt lgkmcnt(5)
	v_mfma_f32_16x16x32_bf16 v[108:111], v[140:143], v[218:221], 0
	v_mfma_f32_16x16x32_bf16 v[104:107], v[186:189], v[218:221], 0
	s_waitcnt lgkmcnt(3)
	v_mfma_f32_16x16x32_bf16 v[92:95], v[140:143], v[226:229], 0
	v_mfma_f32_16x16x32_bf16 v[88:91], v[186:189], v[226:229], 0
	s_waitcnt lgkmcnt(1)
	v_mfma_f32_16x16x32_bf16 v[76:79], v[140:143], v[234:237], 0
	v_mfma_f32_16x16x32_bf16 v[72:75], v[186:189], v[234:237], 0
	v_mfma_f32_16x16x32_bf16 v[124:127], v[144:147], v[214:217], v[124:127]
	v_mfma_f32_16x16x32_bf16 v[120:123], v[190:193], v[214:217], v[120:123]
	v_mfma_f32_16x16x32_bf16 v[108:111], v[144:147], v[222:225], v[108:111]
	v_mfma_f32_16x16x32_bf16 v[104:107], v[190:193], v[222:225], v[104:107]
	v_mfma_f32_16x16x32_bf16 v[92:95], v[144:147], v[230:233], v[92:95]
	v_mfma_f32_16x16x32_bf16 v[88:91], v[190:193], v[230:233], v[88:91]
	s_waitcnt lgkmcnt(0)
	v_mfma_f32_16x16x32_bf16 v[76:79], v[144:147], v[238:241], v[76:79]
	v_mfma_f32_16x16x32_bf16 v[72:75], v[190:193], v[238:241], v[72:75]
	s_setprio 0
	s_setprio 1
	v_mfma_f32_16x16x32_bf16 v[116:119], v[194:197], v[210:213], 0
	v_mfma_f32_16x16x32_bf16 v[112:115], v[202:205], v[210:213], 0
	v_mfma_f32_16x16x32_bf16 v[100:103], v[194:197], v[218:221], 0
	v_mfma_f32_16x16x32_bf16 v[96:99], v[202:205], v[218:221], 0
	v_mfma_f32_16x16x32_bf16 v[84:87], v[194:197], v[226:229], 0
	v_mfma_f32_16x16x32_bf16 v[80:83], v[202:205], v[226:229], 0
	v_mfma_f32_16x16x32_bf16 v[68:71], v[194:197], v[234:237], 0
	v_mfma_f32_16x16x32_bf16 v[64:67], v[202:205], v[234:237], 0
	v_mfma_f32_16x16x32_bf16 v[116:119], v[198:201], v[214:217], v[116:119]
	v_mfma_f32_16x16x32_bf16 v[112:115], v[206:209], v[214:217], v[112:115]
	v_mfma_f32_16x16x32_bf16 v[100:103], v[198:201], v[222:225], v[100:103]
	v_mfma_f32_16x16x32_bf16 v[96:99], v[206:209], v[222:225], v[96:99]
	v_mfma_f32_16x16x32_bf16 v[84:87], v[198:201], v[230:233], v[84:87]
	v_mfma_f32_16x16x32_bf16 v[80:83], v[206:209], v[230:233], v[80:83]
	v_mfma_f32_16x16x32_bf16 v[68:71], v[198:201], v[238:241], v[68:71]
	v_mfma_f32_16x16x32_bf16 v[64:67], v[206:209], v[238:241], v[64:67]
	s_setprio 0
	s_barrier
	ds_read_b128 v[210:213], v166 offset:16384
	ds_read_b128 v[214:217], v166 offset:17408
	ds_read_b128 v[218:221], v166 offset:18432
	ds_read_b128 v[222:225], v166 offset:19456
	ds_read_b128 v[226:229], v166 offset:20480
	ds_read_b128 v[230:233], v166 offset:21504
	ds_read_b128 v[234:237], v166 offset:22528
	ds_read_b128 v[238:241], v166 offset:23552
	v_readfirstlane_b32 s64, v169
	s_mov_b32 s65, m0
	s_mov_b32 m0, s64
	s_nop 0
	global_load_lds_dwordx4 v152, s[68:69]
	s_mov_b32 m0, s65
	v_readfirstlane_b32 s64, v170
	s_mov_b32 s65, m0
	s_mov_b32 m0, s64
	s_nop 0
	global_load_lds_dwordx4 v154, s[68:69]
	s_mov_b32 m0, s65
	s_add_u32 s64, s68, 0x40000
	v_readfirstlane_b32 vcc_lo, v171
	s_addc_u32 s65, s69, 0
	s_mov_b32 vcc_hi, m0
	s_mov_b32 m0, vcc_lo
	s_nop 0
	global_load_lds_dwordx4 v152, s[64:65]
	s_mov_b32 m0, vcc_hi
	v_readfirstlane_b32 vcc_lo, v172
	s_mov_b32 vcc_hi, m0
	s_mov_b32 m0, vcc_lo
	s_nop 0
	global_load_lds_dwordx4 v154, s[64:65]
	s_mov_b32 m0, vcc_hi
	v_readfirstlane_b32 s64, v173
	s_mov_b32 s65, m0
	s_mov_b32 m0, s64
	s_nop 0
	global_load_lds_dwordx4 v151, s[70:71]
	s_mov_b32 m0, s65
	v_readfirstlane_b32 s64, v174
	s_mov_b32 s65, m0
	s_mov_b32 m0, s64
	s_nop 0
	global_load_lds_dwordx4 v153, s[70:71]
	s_mov_b32 m0, s65
	s_waitcnt vmcnt(8)
	s_waitcnt lgkmcnt(0)
	s_barrier
	s_setprio 1
	s_waitcnt lgkmcnt(7)
	v_mfma_f32_16x16x32_bf16 v[60:63], v[140:143], v[210:213], 0
	v_mfma_f32_16x16x32_bf16 v[56:59], v[186:189], v[210:213], 0
	s_waitcnt lgkmcnt(5)
	v_mfma_f32_16x16x32_bf16 v[44:47], v[140:143], v[218:221], 0
	v_mfma_f32_16x16x32_bf16 v[40:43], v[186:189], v[218:221], 0
	s_waitcnt lgkmcnt(3)
	v_mfma_f32_16x16x32_bf16 v[28:31], v[140:143], v[226:229], 0
	v_mfma_f32_16x16x32_bf16 v[24:27], v[186:189], v[226:229], 0
	s_waitcnt lgkmcnt(1)
	v_mfma_f32_16x16x32_bf16 v[12:15], v[140:143], v[234:237], 0
	v_mfma_f32_16x16x32_bf16 v[8:11], v[186:189], v[234:237], 0
	v_mfma_f32_16x16x32_bf16 v[60:63], v[144:147], v[214:217], v[60:63]
	v_mfma_f32_16x16x32_bf16 v[56:59], v[190:193], v[214:217], v[56:59]
	v_mfma_f32_16x16x32_bf16 v[44:47], v[144:147], v[222:225], v[44:47]
	v_mfma_f32_16x16x32_bf16 v[40:43], v[190:193], v[222:225], v[40:43]
	v_mfma_f32_16x16x32_bf16 v[28:31], v[144:147], v[230:233], v[28:31]
	v_mfma_f32_16x16x32_bf16 v[24:27], v[190:193], v[230:233], v[24:27]
	s_waitcnt lgkmcnt(0)
	v_mfma_f32_16x16x32_bf16 v[12:15], v[144:147], v[238:241], v[12:15]
	v_mfma_f32_16x16x32_bf16 v[8:11], v[190:193], v[238:241], v[8:11]
	s_setprio 0
	s_setprio 1
	v_mfma_f32_16x16x32_bf16 v[52:55], v[194:197], v[210:213], 0
	v_mfma_f32_16x16x32_bf16 v[48:51], v[202:205], v[210:213], 0
	v_mfma_f32_16x16x32_bf16 v[36:39], v[194:197], v[218:221], 0
	v_mfma_f32_16x16x32_bf16 v[32:35], v[202:205], v[218:221], 0
	v_mfma_f32_16x16x32_bf16 v[20:23], v[194:197], v[226:229], 0
	v_mfma_f32_16x16x32_bf16 v[16:19], v[202:205], v[226:229], 0
	v_mfma_f32_16x16x32_bf16 v[4:7], v[194:197], v[234:237], 0
	v_mfma_f32_16x16x32_bf16 v[0:3], v[202:205], v[234:237], 0
	v_mfma_f32_16x16x32_bf16 v[52:55], v[198:201], v[214:217], v[52:55]
	v_mfma_f32_16x16x32_bf16 v[48:51], v[206:209], v[214:217], v[48:51]
	v_mfma_f32_16x16x32_bf16 v[36:39], v[198:201], v[222:225], v[36:39]
	v_mfma_f32_16x16x32_bf16 v[32:35], v[206:209], v[222:225], v[32:35]
	v_mfma_f32_16x16x32_bf16 v[20:23], v[198:201], v[230:233], v[20:23]
	v_mfma_f32_16x16x32_bf16 v[16:19], v[206:209], v[230:233], v[16:19]
	v_mfma_f32_16x16x32_bf16 v[4:7], v[198:201], v[238:241], v[4:7]
	v_mfma_f32_16x16x32_bf16 v[0:3], v[206:209], v[238:241], v[0:3]
	s_setprio 0
	s_barrier
	ds_read_b128 v[140:143], v175
	ds_read_b128 v[144:147], v175 offset:1024
	ds_read_b128 v[186:189], v175 offset:2048
	ds_read_b128 v[190:193], v175 offset:3072
	ds_read_b128 v[194:197], v177
	ds_read_b128 v[198:201], v177 offset:1024
	ds_read_b128 v[202:205], v177 offset:2048
	ds_read_b128 v[206:209], v177 offset:3072
	ds_read_b128 v[210:213], v166 offset:32768
	ds_read_b128 v[214:217], v166 offset:33792
	ds_read_b128 v[218:221], v166 offset:34816
	ds_read_b128 v[222:225], v166 offset:35840
	ds_read_b128 v[226:229], v166 offset:36864
	ds_read_b128 v[230:233], v166 offset:37888
	ds_read_b128 v[234:237], v166 offset:38912
	ds_read_b128 v[238:241], v166 offset:39936
	s_add_u32 s64, s70, 0x40000
	s_addc_u32 s65, s71, 0
	v_readfirstlane_b32 s70, v178
	s_mov_b32 s71, m0
	s_mov_b32 m0, s70
	s_nop 0
	global_load_lds_dwordx4 v151, s[64:65]
	s_mov_b32 m0, s71
	v_readfirstlane_b32 s70, v179
	s_mov_b32 s71, m0
	s_mov_b32 m0, s70
	s_nop 0
	global_load_lds_dwordx4 v153, s[64:65]
	s_mov_b32 m0, s71
	s_waitcnt vmcnt(8)
	s_waitcnt lgkmcnt(0)
	s_barrier
	s_setprio 1
	s_waitcnt lgkmcnt(7)
	v_mfma_f32_16x16x32_bf16 v[124:127], v[140:143], v[210:213], v[124:127]
	v_mfma_f32_16x16x32_bf16 v[120:123], v[186:189], v[210:213], v[120:123]
	s_waitcnt lgkmcnt(5)
	v_mfma_f32_16x16x32_bf16 v[108:111], v[140:143], v[218:221], v[108:111]
	v_mfma_f32_16x16x32_bf16 v[104:107], v[186:189], v[218:221], v[104:107]
	s_waitcnt lgkmcnt(3)
	v_mfma_f32_16x16x32_bf16 v[92:95], v[140:143], v[226:229], v[92:95]
	v_mfma_f32_16x16x32_bf16 v[88:91], v[186:189], v[226:229], v[88:91]
	s_waitcnt lgkmcnt(1)
	v_mfma_f32_16x16x32_bf16 v[76:79], v[140:143], v[234:237], v[76:79]
	v_mfma_f32_16x16x32_bf16 v[72:75], v[186:189], v[234:237], v[72:75]
	v_mfma_f32_16x16x32_bf16 v[124:127], v[144:147], v[214:217], v[124:127]
	v_mfma_f32_16x16x32_bf16 v[120:123], v[190:193], v[214:217], v[120:123]
	v_mfma_f32_16x16x32_bf16 v[108:111], v[144:147], v[222:225], v[108:111]
	v_mfma_f32_16x16x32_bf16 v[104:107], v[190:193], v[222:225], v[104:107]
	v_mfma_f32_16x16x32_bf16 v[92:95], v[144:147], v[230:233], v[92:95]
	v_mfma_f32_16x16x32_bf16 v[88:91], v[190:193], v[230:233], v[88:91]
	s_waitcnt lgkmcnt(0)
	v_mfma_f32_16x16x32_bf16 v[76:79], v[144:147], v[238:241], v[76:79]
	v_mfma_f32_16x16x32_bf16 v[72:75], v[190:193], v[238:241], v[72:75]
	s_setprio 0
	s_setprio 1
	v_mfma_f32_16x16x32_bf16 v[116:119], v[194:197], v[210:213], v[116:119]
	v_mfma_f32_16x16x32_bf16 v[112:115], v[202:205], v[210:213], v[112:115]
	v_mfma_f32_16x16x32_bf16 v[100:103], v[194:197], v[218:221], v[100:103]
	v_mfma_f32_16x16x32_bf16 v[96:99], v[202:205], v[218:221], v[96:99]
	v_mfma_f32_16x16x32_bf16 v[84:87], v[194:197], v[226:229], v[84:87]
	v_mfma_f32_16x16x32_bf16 v[80:83], v[202:205], v[226:229], v[80:83]
	v_mfma_f32_16x16x32_bf16 v[68:71], v[194:197], v[234:237], v[68:71]
	v_mfma_f32_16x16x32_bf16 v[64:67], v[202:205], v[234:237], v[64:67]
	v_mfma_f32_16x16x32_bf16 v[116:119], v[198:201], v[214:217], v[116:119]
	v_mfma_f32_16x16x32_bf16 v[112:115], v[206:209], v[214:217], v[112:115]
	v_mfma_f32_16x16x32_bf16 v[100:103], v[198:201], v[222:225], v[100:103]
	v_mfma_f32_16x16x32_bf16 v[96:99], v[206:209], v[222:225], v[96:99]
	v_mfma_f32_16x16x32_bf16 v[84:87], v[198:201], v[230:233], v[84:87]
	v_mfma_f32_16x16x32_bf16 v[80:83], v[206:209], v[230:233], v[80:83]
	v_mfma_f32_16x16x32_bf16 v[68:71], v[198:201], v[238:241], v[68:71]
	v_mfma_f32_16x16x32_bf16 v[64:67], v[206:209], v[238:241], v[64:67]
	s_setprio 0
	s_barrier
	ds_read_b128 v[210:213], v166 offset:49152
	ds_read_b128 v[214:217], v166 offset:50176
	ds_read_b128 v[218:221], v166 offset:51200
	ds_read_b128 v[222:225], v166 offset:52224
	ds_read_b128 v[226:229], v166 offset:53248
	ds_read_b128 v[230:233], v166 offset:54272
	ds_read_b128 v[234:237], v166 offset:55296
	ds_read_b128 v[238:241], v166 offset:56320
	s_add_u32 s64, s68, 0x80
	s_addc_u32 s65, s69, 0
	v_readfirstlane_b32 s70, v156
	s_mov_b32 s71, m0
	s_mov_b32 m0, s70
	s_nop 0
	global_load_lds_dwordx4 v152, s[64:65]
	s_mov_b32 m0, s71
	v_readfirstlane_b32 s70, v157
	s_mov_b32 s71, m0
	s_mov_b32 m0, s70
	s_nop 0
	global_load_lds_dwordx4 v154, s[64:65]
	s_mov_b32 m0, s71
	s_add_u32 s64, s68, 0x40080
	s_addc_u32 s65, s69, 0
	v_readfirstlane_b32 s68, v161
	s_mov_b32 s69, m0
	s_mov_b32 m0, s68
	s_nop 0
	global_load_lds_dwordx4 v152, s[64:65]
	s_mov_b32 m0, s69
	v_readfirstlane_b32 s68, v163
	s_mov_b32 s69, m0
	s_mov_b32 m0, s68
	s_nop 0
	global_load_lds_dwordx4 v154, s[64:65]
	s_mov_b32 m0, s69
	v_readfirstlane_b32 s64, v158
	s_mov_b32 s65, m0
	s_mov_b32 m0, s64
	s_nop 0
	global_load_lds_dwordx4 v151, s[66:67]
	s_mov_b32 m0, s65
	v_readfirstlane_b32 s64, v159
	s_mov_b32 s65, m0
	s_mov_b32 m0, s64
	s_nop 0
	global_load_lds_dwordx4 v153, s[66:67]
	s_mov_b32 m0, s65
	s_waitcnt vmcnt(8)
	s_waitcnt lgkmcnt(0)
	s_barrier
	s_setprio 1
	s_waitcnt lgkmcnt(7)
	v_mfma_f32_16x16x32_bf16 v[60:63], v[140:143], v[210:213], v[60:63]
	v_mfma_f32_16x16x32_bf16 v[56:59], v[186:189], v[210:213], v[56:59]
	s_waitcnt lgkmcnt(5)
	v_mfma_f32_16x16x32_bf16 v[44:47], v[140:143], v[218:221], v[44:47]
	v_mfma_f32_16x16x32_bf16 v[40:43], v[186:189], v[218:221], v[40:43]
	s_waitcnt lgkmcnt(3)
	v_mfma_f32_16x16x32_bf16 v[28:31], v[140:143], v[226:229], v[28:31]
	v_mfma_f32_16x16x32_bf16 v[24:27], v[186:189], v[226:229], v[24:27]
	s_waitcnt lgkmcnt(1)
	v_mfma_f32_16x16x32_bf16 v[12:15], v[140:143], v[234:237], v[12:15]
	v_mfma_f32_16x16x32_bf16 v[8:11], v[186:189], v[234:237], v[8:11]
	v_mfma_f32_16x16x32_bf16 v[60:63], v[144:147], v[214:217], v[60:63]
	v_mfma_f32_16x16x32_bf16 v[56:59], v[190:193], v[214:217], v[56:59]
	v_mfma_f32_16x16x32_bf16 v[44:47], v[144:147], v[222:225], v[44:47]
	v_mfma_f32_16x16x32_bf16 v[40:43], v[190:193], v[222:225], v[40:43]
	v_mfma_f32_16x16x32_bf16 v[28:31], v[144:147], v[230:233], v[28:31]
	v_mfma_f32_16x16x32_bf16 v[24:27], v[190:193], v[230:233], v[24:27]
	s_waitcnt lgkmcnt(0)
	v_mfma_f32_16x16x32_bf16 v[12:15], v[144:147], v[238:241], v[12:15]
	v_mfma_f32_16x16x32_bf16 v[8:11], v[190:193], v[238:241], v[8:11]
	s_setprio 0
	s_setprio 1
	v_mfma_f32_16x16x32_bf16 v[52:55], v[194:197], v[210:213], v[52:55]
	v_mfma_f32_16x16x32_bf16 v[48:51], v[202:205], v[210:213], v[48:51]
	v_mfma_f32_16x16x32_bf16 v[36:39], v[194:197], v[218:221], v[36:39]
	v_mfma_f32_16x16x32_bf16 v[32:35], v[202:205], v[218:221], v[32:35]
	v_mfma_f32_16x16x32_bf16 v[20:23], v[194:197], v[226:229], v[20:23]
	v_mfma_f32_16x16x32_bf16 v[16:19], v[202:205], v[226:229], v[16:19]
	v_mfma_f32_16x16x32_bf16 v[4:7], v[194:197], v[234:237], v[4:7]
	v_mfma_f32_16x16x32_bf16 v[0:3], v[202:205], v[234:237], v[0:3]
	v_mfma_f32_16x16x32_bf16 v[52:55], v[198:201], v[214:217], v[52:55]
	v_mfma_f32_16x16x32_bf16 v[48:51], v[206:209], v[214:217], v[48:51]
	v_mfma_f32_16x16x32_bf16 v[36:39], v[198:201], v[222:225], v[36:39]
	v_mfma_f32_16x16x32_bf16 v[32:35], v[206:209], v[222:225], v[32:35]
	v_mfma_f32_16x16x32_bf16 v[20:23], v[198:201], v[230:233], v[20:23]
	v_mfma_f32_16x16x32_bf16 v[16:19], v[206:209], v[230:233], v[16:19]
	v_mfma_f32_16x16x32_bf16 v[4:7], v[198:201], v[238:241], v[4:7]
	v_mfma_f32_16x16x32_bf16 v[0:3], v[206:209], v[238:241], v[0:3]
	s_setprio 0
	s_barrier
	s_add_i32 s97, s97, 2
	s_add_u32 s95, s95, 0x100
	s_addc_u32 s96, s96, 0
	s_cmp_gt_u32 s97, 13
	s_mov_b64 s[64:65], s[54:55]
	s_branch .LBB0_132

.LBB0_412:
	s_ashr_i32 s23, s22, 31
	s_lshl_b64 s[24:25], s[22:23], 18
	s_add_u32 s24, s6, s24
	s_addc_u32 s25, s7, s25
	s_and_b64 s[26:27], s[4:5], exec
	s_cselect_b32 s23, s25, s31
	s_cselect_b32 s51, s24, s30
	s_ashr_i32 s19, s18, 31
	s_lshl_b64 s[26:27], s[18:19], 18
	s_add_u32 s26, s38, s26
	s_addc_u32 s27, s39, s27
	s_and_b64 s[36:37], s[4:5], exec
	s_cselect_b32 s19, s27, s35
	s_cselect_b32 s52, s26, s34
	s_add_u32 s53, s34, 0x100
	s_addc_u32 s54, s35, 0
	s_mov_b32 s55, -2
	ds_read_b128 v[128:131], v175
	ds_read_b128 v[132:135], v175 offset:1024
	ds_read_b128 v[136:139], v175 offset:2048
	ds_read_b128 v[140:143], v175 offset:3072
	ds_read_b128 v[148:151], v176
	ds_read_b128 v[152:155], v176 offset:1024
	ds_read_b128 v[156:159], v176 offset:2048
	ds_read_b128 v[190:193], v176 offset:3072
	s_add_u32 s34, s30, 0x100
	s_addc_u32 s35, s31, 0
	s_cmp_eq_u32 s55, 4
	s_cselect_b32 s44, s51, s34
	s_cselect_b32 s45, s23, s35
	s_cselect_b32 s42, s52, s53
	s_cselect_b32 s43, s19, s54
	s_add_u32 s36, s44, 0x80
	s_addc_u32 s37, s45, 0
	ds_read_b128 v[194:197], v177
	ds_read_b128 v[198:201], v177 offset:1024
	ds_read_b128 v[202:205], v177 offset:2048
	ds_read_b128 v[206:209], v177 offset:3072
	ds_read_b128 v[210:213], v177 offset:4096
	ds_read_b128 v[214:217], v177 offset:5120
	ds_read_b128 v[218:221], v177 offset:6144
	ds_read_b128 v[222:225], v177 offset:7168
	s_add_u32 s30, s30, 0x20080
	v_readfirstlane_b32 s56, v178
	s_addc_u32 s31, s31, 0
	s_mov_b32 s57, m0
	s_mov_b32 m0, s56
	s_nop 0
	global_load_lds_dwordx4 v160, s[30:31]
	s_mov_b32 m0, s57
	v_readfirstlane_b32 s56, v179
	s_add_i32 s56, s56, 0
	s_add_i32 s56, s56, 0xe000
	s_mov_b32 s57, m0
	s_mov_b32 m0, s56
	s_nop 0
	global_load_lds_dwordx4 v162, s[30:31]
	s_mov_b32 m0, s57
	s_waitcnt vmcnt(8)
	s_waitcnt lgkmcnt(0)
	s_barrier
	s_setprio 1
	s_waitcnt lgkmcnt(7)
	v_mfma_f32_16x16x32_bf16 v[124:127], v[128:131], v[194:197], 0
	v_mfma_f32_16x16x32_bf16 v[120:123], v[136:139], v[194:197], 0
	s_waitcnt lgkmcnt(5)
	v_mfma_f32_16x16x32_bf16 v[116:119], v[128:131], v[202:205], 0
	v_mfma_f32_16x16x32_bf16 v[112:115], v[136:139], v[202:205], 0
	s_waitcnt lgkmcnt(3)
	v_mfma_f32_16x16x32_bf16 v[108:111], v[128:131], v[210:213], 0
	v_mfma_f32_16x16x32_bf16 v[104:107], v[136:139], v[210:213], 0
	s_waitcnt lgkmcnt(1)
	v_mfma_f32_16x16x32_bf16 v[100:103], v[128:131], v[218:221], 0
	v_mfma_f32_16x16x32_bf16 v[96:99], v[136:139], v[218:221], 0
	v_mfma_f32_16x16x32_bf16 v[124:127], v[132:135], v[198:201], v[124:127]
	v_mfma_f32_16x16x32_bf16 v[120:123], v[140:143], v[198:201], v[120:123]
	v_mfma_f32_16x16x32_bf16 v[116:119], v[132:135], v[206:209], v[116:119]
	v_mfma_f32_16x16x32_bf16 v[112:115], v[140:143], v[206:209], v[112:115]
	v_mfma_f32_16x16x32_bf16 v[108:111], v[132:135], v[214:217], v[108:111]
	v_mfma_f32_16x16x32_bf16 v[104:107], v[140:143], v[214:217], v[104:107]
	s_waitcnt lgkmcnt(0)
	v_mfma_f32_16x16x32_bf16 v[100:103], v[132:135], v[222:225], v[100:103]
	v_mfma_f32_16x16x32_bf16 v[96:99], v[140:143], v[222:225], v[96:99]
	s_setprio 0
	s_setprio 1
	v_mfma_f32_16x16x32_bf16 v[60:63], v[148:151], v[194:197], 0
	v_mfma_f32_16x16x32_bf16 v[56:59], v[156:159], v[194:197], 0
	v_mfma_f32_16x16x32_bf16 v[52:55], v[148:151], v[202:205], 0
	v_mfma_f32_16x16x32_bf16 v[48:51], v[156:159], v[202:205], 0
	v_mfma_f32_16x16x32_bf16 v[44:47], v[148:151], v[210:213], 0
	v_mfma_f32_16x16x32_bf16 v[40:43], v[156:159], v[210:213], 0
	v_mfma_f32_16x16x32_bf16 v[36:39], v[148:151], v[218:221], 0
	v_mfma_f32_16x16x32_bf16 v[32:35], v[156:159], v[218:221], 0
	v_mfma_f32_16x16x32_bf16 v[60:63], v[152:155], v[198:201], v[60:63]
	v_mfma_f32_16x16x32_bf16 v[56:59], v[190:193], v[198:201], v[56:59]
	v_mfma_f32_16x16x32_bf16 v[52:55], v[152:155], v[206:209], v[52:55]
	v_mfma_f32_16x16x32_bf16 v[48:51], v[190:193], v[206:209], v[48:51]
	v_mfma_f32_16x16x32_bf16 v[44:47], v[152:155], v[214:217], v[44:47]
	v_mfma_f32_16x16x32_bf16 v[40:43], v[190:193], v[214:217], v[40:43]
	v_mfma_f32_16x16x32_bf16 v[36:39], v[152:155], v[222:225], v[36:39]
	v_mfma_f32_16x16x32_bf16 v[32:35], v[190:193], v[222:225], v[32:35]
	s_setprio 0
	s_barrier
	ds_read_b128 v[194:197], v177 offset:16384
	ds_read_b128 v[198:201], v177 offset:17408
	ds_read_b128 v[202:205], v177 offset:18432
	ds_read_b128 v[206:209], v177 offset:19456
	ds_read_b128 v[210:213], v177 offset:20480
	ds_read_b128 v[214:217], v177 offset:21504
	ds_read_b128 v[218:221], v177 offset:22528
	ds_read_b128 v[222:225], v177 offset:23552
	v_readfirstlane_b32 s30, v180
	s_mov_b32 s31, m0
	s_mov_b32 m0, s30
	s_nop 0
	global_load_lds_dwordx4 v161, s[42:43]
	s_mov_b32 m0, s31
	v_readfirstlane_b32 s30, v181
	s_mov_b32 s31, m0
	s_mov_b32 m0, s30
	s_nop 0
	global_load_lds_dwordx4 v164, s[42:43]
	s_mov_b32 m0, s31
	s_add_u32 s30, s42, 0x20000
	s_addc_u32 s31, s43, 0
	v_readfirstlane_b32 s56, v182
	s_mov_b32 s57, m0
	s_mov_b32 m0, s56
	s_nop 0
	global_load_lds_dwordx4 v161, s[30:31]
	s_mov_b32 m0, s57
	v_readfirstlane_b32 s56, v183
	s_mov_b32 s57, m0
	s_mov_b32 m0, s56
	s_nop 0
	global_load_lds_dwordx4 v164, s[30:31]
	s_mov_b32 m0, s57
	v_readfirstlane_b32 s30, v184
	s_mov_b32 s31, m0
	s_mov_b32 m0, s30
	s_nop 0
	global_load_lds_dwordx4 v160, s[44:45]
	s_mov_b32 m0, s31
	v_readfirstlane_b32 s30, v185
	s_mov_b32 s31, m0
	s_mov_b32 m0, s30
	s_nop 0
	global_load_lds_dwordx4 v162, s[44:45]
	s_mov_b32 m0, s31
	s_waitcnt vmcnt(8)
	s_waitcnt lgkmcnt(0)
	s_barrier
	s_setprio 1
	s_waitcnt lgkmcnt(7)
	v_mfma_f32_16x16x32_bf16 v[92:95], v[128:131], v[194:197], 0
	v_mfma_f32_16x16x32_bf16 v[88:91], v[136:139], v[194:197], 0
	s_waitcnt lgkmcnt(5)
	v_mfma_f32_16x16x32_bf16 v[84:87], v[128:131], v[202:205], 0
	v_mfma_f32_16x16x32_bf16 v[80:83], v[136:139], v[202:205], 0
	s_waitcnt lgkmcnt(3)
	v_mfma_f32_16x16x32_bf16 v[76:79], v[128:131], v[210:213], 0
	v_mfma_f32_16x16x32_bf16 v[72:75], v[136:139], v[210:213], 0
	s_waitcnt lgkmcnt(1)
	v_mfma_f32_16x16x32_bf16 v[68:71], v[128:131], v[218:221], 0
	v_mfma_f32_16x16x32_bf16 v[64:67], v[136:139], v[218:221], 0
	v_mfma_f32_16x16x32_bf16 v[92:95], v[132:135], v[198:201], v[92:95]
	v_mfma_f32_16x16x32_bf16 v[88:91], v[140:143], v[198:201], v[88:91]
	v_mfma_f32_16x16x32_bf16 v[84:87], v[132:135], v[206:209], v[84:87]
	v_mfma_f32_16x16x32_bf16 v[80:83], v[140:143], v[206:209], v[80:83]
	v_mfma_f32_16x16x32_bf16 v[76:79], v[132:135], v[214:217], v[76:79]
	v_mfma_f32_16x16x32_bf16 v[72:75], v[140:143], v[214:217], v[72:75]
	s_waitcnt lgkmcnt(0)
	v_mfma_f32_16x16x32_bf16 v[68:71], v[132:135], v[222:225], v[68:71]
	v_mfma_f32_16x16x32_bf16 v[64:67], v[140:143], v[222:225], v[64:67]
	s_setprio 0
	s_setprio 1
	v_mfma_f32_16x16x32_bf16 v[28:31], v[148:151], v[194:197], 0
	v_mfma_f32_16x16x32_bf16 v[24:27], v[156:159], v[194:197], 0
	v_mfma_f32_16x16x32_bf16 v[20:23], v[148:151], v[202:205], 0
	v_mfma_f32_16x16x32_bf16 v[16:19], v[156:159], v[202:205], 0
	v_mfma_f32_16x16x32_bf16 v[12:15], v[148:151], v[210:213], 0
	v_mfma_f32_16x16x32_bf16 v[8:11], v[156:159], v[210:213], 0
	v_mfma_f32_16x16x32_bf16 v[4:7], v[148:151], v[218:221], 0
	v_mfma_f32_16x16x32_bf16 v[0:3], v[156:159], v[218:221], 0
	v_mfma_f32_16x16x32_bf16 v[28:31], v[152:155], v[198:201], v[28:31]
	v_mfma_f32_16x16x32_bf16 v[24:27], v[190:193], v[198:201], v[24:27]
	v_mfma_f32_16x16x32_bf16 v[20:23], v[152:155], v[206:209], v[20:23]
	v_mfma_f32_16x16x32_bf16 v[16:19], v[190:193], v[206:209], v[16:19]
	v_mfma_f32_16x16x32_bf16 v[12:15], v[152:155], v[214:217], v[12:15]
	v_mfma_f32_16x16x32_bf16 v[8:11], v[190:193], v[214:217], v[8:11]
	v_mfma_f32_16x16x32_bf16 v[4:7], v[152:155], v[222:225], v[4:7]
	v_mfma_f32_16x16x32_bf16 v[0:3], v[190:193], v[222:225], v[0:3]
	s_setprio 0
	s_barrier
	ds_read_b128 v[128:131], v186
	ds_read_b128 v[132:135], v186 offset:1024
	ds_read_b128 v[136:139], v186 offset:2048
	ds_read_b128 v[140:143], v186 offset:3072
	ds_read_b128 v[148:151], v187
	ds_read_b128 v[152:155], v187 offset:1024
	ds_read_b128 v[156:159], v187 offset:2048
	ds_read_b128 v[190:193], v187 offset:3072
	ds_read_b128 v[194:197], v177 offset:32768
	ds_read_b128 v[198:201], v177 offset:33792
	ds_read_b128 v[202:205], v177 offset:34816
	ds_read_b128 v[206:209], v177 offset:35840
	ds_read_b128 v[210:213], v177 offset:36864
	ds_read_b128 v[214:217], v177 offset:37888
	ds_read_b128 v[218:221], v177 offset:38912
	ds_read_b128 v[222:225], v177 offset:39936
	s_add_u32 s30, s44, 0x20000
	s_addc_u32 s31, s45, 0
	v_readfirstlane_b32 s44, v188
	s_mov_b32 s45, m0
	s_mov_b32 m0, s44
	s_nop 0
	global_load_lds_dwordx4 v160, s[30:31]
	s_mov_b32 m0, s45
	v_readfirstlane_b32 s44, v189
	s_mov_b32 s45, m0
	s_mov_b32 m0, s44
	s_nop 0
	global_load_lds_dwordx4 v162, s[30:31]
	s_mov_b32 m0, s45
	s_waitcnt vmcnt(8)
	s_waitcnt lgkmcnt(0)
	s_barrier
	s_setprio 1
	s_waitcnt lgkmcnt(7)
	v_mfma_f32_16x16x32_bf16 v[124:127], v[128:131], v[194:197], v[124:127]
	v_mfma_f32_16x16x32_bf16 v[120:123], v[136:139], v[194:197], v[120:123]
	s_waitcnt lgkmcnt(5)
	v_mfma_f32_16x16x32_bf16 v[116:119], v[128:131], v[202:205], v[116:119]
	v_mfma_f32_16x16x32_bf16 v[112:115], v[136:139], v[202:205], v[112:115]
	s_waitcnt lgkmcnt(3)
	v_mfma_f32_16x16x32_bf16 v[108:111], v[128:131], v[210:213], v[108:111]
	v_mfma_f32_16x16x32_bf16 v[104:107], v[136:139], v[210:213], v[104:107]
	s_waitcnt lgkmcnt(1)
	v_mfma_f32_16x16x32_bf16 v[100:103], v[128:131], v[218:221], v[100:103]
	v_mfma_f32_16x16x32_bf16 v[96:99], v[136:139], v[218:221], v[96:99]
	v_mfma_f32_16x16x32_bf16 v[124:127], v[132:135], v[198:201], v[124:127]
	v_mfma_f32_16x16x32_bf16 v[120:123], v[140:143], v[198:201], v[120:123]
	v_mfma_f32_16x16x32_bf16 v[116:119], v[132:135], v[206:209], v[116:119]
	v_mfma_f32_16x16x32_bf16 v[112:115], v[140:143], v[206:209], v[112:115]
	v_mfma_f32_16x16x32_bf16 v[108:111], v[132:135], v[214:217], v[108:111]
	v_mfma_f32_16x16x32_bf16 v[104:107], v[140:143], v[214:217], v[104:107]
	s_waitcnt lgkmcnt(0)
	v_mfma_f32_16x16x32_bf16 v[100:103], v[132:135], v[222:225], v[100:103]
	v_mfma_f32_16x16x32_bf16 v[96:99], v[140:143], v[222:225], v[96:99]
	s_setprio 0
	s_setprio 1
	v_mfma_f32_16x16x32_bf16 v[60:63], v[148:151], v[194:197], v[60:63]
	v_mfma_f32_16x16x32_bf16 v[56:59], v[156:159], v[194:197], v[56:59]
	v_mfma_f32_16x16x32_bf16 v[52:55], v[148:151], v[202:205], v[52:55]
	v_mfma_f32_16x16x32_bf16 v[48:51], v[156:159], v[202:205], v[48:51]
	v_mfma_f32_16x16x32_bf16 v[44:47], v[148:151], v[210:213], v[44:47]
	v_mfma_f32_16x16x32_bf16 v[40:43], v[156:159], v[210:213], v[40:43]
	v_mfma_f32_16x16x32_bf16 v[36:39], v[148:151], v[218:221], v[36:39]
	v_mfma_f32_16x16x32_bf16 v[32:35], v[156:159], v[218:221], v[32:35]
	v_mfma_f32_16x16x32_bf16 v[60:63], v[152:155], v[198:201], v[60:63]
	v_mfma_f32_16x16x32_bf16 v[56:59], v[190:193], v[198:201], v[56:59]
	v_mfma_f32_16x16x32_bf16 v[52:55], v[152:155], v[206:209], v[52:55]
	v_mfma_f32_16x16x32_bf16 v[48:51], v[190:193], v[206:209], v[48:51]
	v_mfma_f32_16x16x32_bf16 v[44:47], v[152:155], v[214:217], v[44:47]
	v_mfma_f32_16x16x32_bf16 v[40:43], v[190:193], v[214:217], v[40:43]
	v_mfma_f32_16x16x32_bf16 v[36:39], v[152:155], v[222:225], v[36:39]
	v_mfma_f32_16x16x32_bf16 v[32:35], v[190:193], v[222:225], v[32:35]
	s_setprio 0
	s_barrier
	ds_read_b128 v[194:197], v177 offset:49152
	ds_read_b128 v[198:201], v177 offset:50176
	ds_read_b128 v[202:205], v177 offset:51200
	ds_read_b128 v[206:209], v177 offset:52224
	ds_read_b128 v[210:213], v177 offset:53248
	ds_read_b128 v[214:217], v177 offset:54272
	ds_read_b128 v[218:221], v177 offset:55296
	ds_read_b128 v[222:225], v177 offset:56320
	s_add_u32 s30, s42, 0x80
	s_addc_u32 s31, s43, 0
	v_readfirstlane_b32 s44, v167
	s_mov_b32 s45, m0
	s_mov_b32 m0, s44
	s_nop 0
	global_load_lds_dwordx4 v161, s[30:31]
	s_mov_b32 m0, s45
	v_readfirstlane_b32 s44, v168
	s_mov_b32 s45, m0
	s_mov_b32 m0, s44
	s_nop 0
	global_load_lds_dwordx4 v164, s[30:31]
	s_mov_b32 m0, s45
	s_add_u32 s30, s42, 0x20080
	s_addc_u32 s31, s43, 0
	v_readfirstlane_b32 s42, v172
	s_mov_b32 s43, m0
	s_mov_b32 m0, s42
	s_nop 0
	global_load_lds_dwordx4 v161, s[30:31]
	s_mov_b32 m0, s43
	v_readfirstlane_b32 s42, v173
	s_mov_b32 s43, m0
	s_mov_b32 m0, s42
	s_nop 0
	global_load_lds_dwordx4 v164, s[30:31]
	s_mov_b32 m0, s43
	v_readfirstlane_b32 s30, v170
	s_mov_b32 s31, m0
	s_mov_b32 m0, s30
	s_nop 0
	global_load_lds_dwordx4 v160, s[36:37]
	s_mov_b32 m0, s31
	v_readfirstlane_b32 s30, v171
	s_mov_b32 s31, m0
	s_mov_b32 m0, s30
	s_nop 0
	global_load_lds_dwordx4 v162, s[36:37]
	s_mov_b32 m0, s31
	s_waitcnt vmcnt(8)
	s_waitcnt lgkmcnt(0)
	s_barrier
	s_setprio 1
	s_waitcnt lgkmcnt(7)
	v_mfma_f32_16x16x32_bf16 v[92:95], v[128:131], v[194:197], v[92:95]
	v_mfma_f32_16x16x32_bf16 v[88:91], v[136:139], v[194:197], v[88:91]
	s_waitcnt lgkmcnt(5)
	v_mfma_f32_16x16x32_bf16 v[84:87], v[128:131], v[202:205], v[84:87]
	v_mfma_f32_16x16x32_bf16 v[80:83], v[136:139], v[202:205], v[80:83]
	s_waitcnt lgkmcnt(3)
	v_mfma_f32_16x16x32_bf16 v[76:79], v[128:131], v[210:213], v[76:79]
	v_mfma_f32_16x16x32_bf16 v[72:75], v[136:139], v[210:213], v[72:75]
	s_waitcnt lgkmcnt(1)
	v_mfma_f32_16x16x32_bf16 v[68:71], v[128:131], v[218:221], v[68:71]
	v_mfma_f32_16x16x32_bf16 v[64:67], v[136:139], v[218:221], v[64:67]
	v_mfma_f32_16x16x32_bf16 v[92:95], v[132:135], v[198:201], v[92:95]
	v_mfma_f32_16x16x32_bf16 v[88:91], v[140:143], v[198:201], v[88:91]
	v_mfma_f32_16x16x32_bf16 v[84:87], v[132:135], v[206:209], v[84:87]
	v_mfma_f32_16x16x32_bf16 v[80:83], v[140:143], v[206:209], v[80:83]
	v_mfma_f32_16x16x32_bf16 v[76:79], v[132:135], v[214:217], v[76:79]
	v_mfma_f32_16x16x32_bf16 v[72:75], v[140:143], v[214:217], v[72:75]
	s_waitcnt lgkmcnt(0)
	v_mfma_f32_16x16x32_bf16 v[68:71], v[132:135], v[222:225], v[68:71]
	v_mfma_f32_16x16x32_bf16 v[64:67], v[140:143], v[222:225], v[64:67]
	s_setprio 0
	s_setprio 1
	v_mfma_f32_16x16x32_bf16 v[28:31], v[148:151], v[194:197], v[28:31]
	v_mfma_f32_16x16x32_bf16 v[24:27], v[156:159], v[194:197], v[24:27]
	v_mfma_f32_16x16x32_bf16 v[20:23], v[148:151], v[202:205], v[20:23]
	v_mfma_f32_16x16x32_bf16 v[16:19], v[156:159], v[202:205], v[16:19]
	v_mfma_f32_16x16x32_bf16 v[12:15], v[148:151], v[210:213], v[12:15]
	v_mfma_f32_16x16x32_bf16 v[8:11], v[156:159], v[210:213], v[8:11]
	v_mfma_f32_16x16x32_bf16 v[4:7], v[148:151], v[218:221], v[4:7]
	v_mfma_f32_16x16x32_bf16 v[0:3], v[156:159], v[218:221], v[0:3]
	v_mfma_f32_16x16x32_bf16 v[28:31], v[152:155], v[198:201], v[28:31]
	v_mfma_f32_16x16x32_bf16 v[24:27], v[190:193], v[198:201], v[24:27]
	v_mfma_f32_16x16x32_bf16 v[20:23], v[152:155], v[206:209], v[20:23]
	v_mfma_f32_16x16x32_bf16 v[16:19], v[190:193], v[206:209], v[16:19]
	v_mfma_f32_16x16x32_bf16 v[12:15], v[152:155], v[214:217], v[12:15]
	v_mfma_f32_16x16x32_bf16 v[8:11], v[190:193], v[214:217], v[8:11]
	v_mfma_f32_16x16x32_bf16 v[4:7], v[152:155], v[222:225], v[4:7]
	v_mfma_f32_16x16x32_bf16 v[0:3], v[190:193], v[222:225], v[0:3]
	s_setprio 0
	s_barrier
	s_add_i32 s55, s55, 2
	s_add_u32 s53, s53, 0x100
	s_addc_u32 s54, s54, 0
	s_cmp_gt_u32 s55, 5
	s_mov_b64 s[30:31], s[34:35]
	s_branch .LBB0_413

.LBB0_568:
	s_ashr_i32 s17, s16, 31
	s_lshl_b64 s[18:19], s[16:17], 19
	s_add_u32 s18, s48, s18
	s_addc_u32 s19, s49, s19
	s_and_b64 s[20:21], s[6:7], exec
	s_cselect_b32 s17, s19, s27
	s_cselect_b32 s23, s18, s26
	s_ashr_i32 s15, s14, 31
	s_lshl_b64 s[20:21], s[14:15], 19
	s_add_u32 s20, s3, s20
	s_addc_u32 s21, s38, s21
	s_and_b64 s[30:31], s[6:7], exec
	s_cselect_b32 s15, s21, s29
	s_cselect_b32 s44, s20, s28
	s_add_u32 s45, s28, 0x100
	s_addc_u32 s50, s29, 0
	s_mov_b32 s51, -2
	s_waitcnt lgkmcnt(0)
	ds_read_b128 v[132:135], v148
	ds_read_b128 v[170:173], v148 offset:1024
	ds_read_b128 v[174:177], v148 offset:2048
	ds_read_b128 v[178:181], v148 offset:3072
	ds_read_b128 v[182:185], v149
	ds_read_b128 v[186:189], v149 offset:1024
	ds_read_b128 v[190:193], v149 offset:2048
	ds_read_b128 v[194:197], v149 offset:3072
	s_add_u32 s28, s26, 0x100
	s_addc_u32 s29, s27, 0
	s_cmp_eq_u32 s51, 12
	s_cselect_b32 s36, s23, s28
	s_cselect_b32 s37, s17, s29
	s_cselect_b32 s34, s44, s45
	s_cselect_b32 s35, s15, s50
	s_add_u32 s30, s36, 0x80
	s_addc_u32 s31, s37, 0
	ds_read_b128 v[198:201], v150
	ds_read_b128 v[202:205], v150 offset:1024
	ds_read_b128 v[206:209], v150 offset:2048
	ds_read_b128 v[210:213], v150 offset:3072
	ds_read_b128 v[214:217], v150 offset:4096
	ds_read_b128 v[218:221], v150 offset:5120
	ds_read_b128 v[222:225], v150 offset:6144
	ds_read_b128 v[226:229], v150 offset:7168
	s_add_u32 s26, s26, 0x40080
	v_readfirstlane_b32 s52, v151
	s_addc_u32 s27, s27, 0
	s_mov_b32 s53, m0
	s_mov_b32 m0, s52
	s_nop 0
	global_load_lds_dwordx4 v136, s[26:27]
	s_mov_b32 m0, s53
	v_readfirstlane_b32 s52, v152
	s_add_i32 s52, s52, 0
	s_add_i32 s52, s52, 0xe000
	s_mov_b32 s53, m0
	s_mov_b32 m0, s52
	s_nop 0
	global_load_lds_dwordx4 v138, s[26:27]
	s_mov_b32 m0, s53
	s_waitcnt vmcnt(8)
	s_waitcnt lgkmcnt(0)
	s_barrier
	s_setprio 1
	s_waitcnt lgkmcnt(7)
	v_mfma_f32_16x16x32_bf16 v[124:127], v[132:135], v[198:201], 0
	v_mfma_f32_16x16x32_bf16 v[120:123], v[174:177], v[198:201], 0
	s_waitcnt lgkmcnt(5)
	v_mfma_f32_16x16x32_bf16 v[108:111], v[132:135], v[206:209], 0
	v_mfma_f32_16x16x32_bf16 v[104:107], v[174:177], v[206:209], 0
	s_waitcnt lgkmcnt(3)
	v_mfma_f32_16x16x32_bf16 v[92:95], v[132:135], v[214:217], 0
	v_mfma_f32_16x16x32_bf16 v[88:91], v[174:177], v[214:217], 0
	s_waitcnt lgkmcnt(1)
	v_mfma_f32_16x16x32_bf16 v[76:79], v[132:135], v[222:225], 0
	v_mfma_f32_16x16x32_bf16 v[72:75], v[174:177], v[222:225], 0
	v_mfma_f32_16x16x32_bf16 v[124:127], v[170:173], v[202:205], v[124:127]
	v_mfma_f32_16x16x32_bf16 v[120:123], v[178:181], v[202:205], v[120:123]
	v_mfma_f32_16x16x32_bf16 v[108:111], v[170:173], v[210:213], v[108:111]
	v_mfma_f32_16x16x32_bf16 v[104:107], v[178:181], v[210:213], v[104:107]
	v_mfma_f32_16x16x32_bf16 v[92:95], v[170:173], v[218:221], v[92:95]
	v_mfma_f32_16x16x32_bf16 v[88:91], v[178:181], v[218:221], v[88:91]
	s_waitcnt lgkmcnt(0)
	v_mfma_f32_16x16x32_bf16 v[76:79], v[170:173], v[226:229], v[76:79]
	v_mfma_f32_16x16x32_bf16 v[72:75], v[178:181], v[226:229], v[72:75]
	s_setprio 0
	s_setprio 1
	v_mfma_f32_16x16x32_bf16 v[116:119], v[182:185], v[198:201], 0
	v_mfma_f32_16x16x32_bf16 v[112:115], v[190:193], v[198:201], 0
	v_mfma_f32_16x16x32_bf16 v[100:103], v[182:185], v[206:209], 0
	v_mfma_f32_16x16x32_bf16 v[96:99], v[190:193], v[206:209], 0
	v_mfma_f32_16x16x32_bf16 v[84:87], v[182:185], v[214:217], 0
	v_mfma_f32_16x16x32_bf16 v[80:83], v[190:193], v[214:217], 0
	v_mfma_f32_16x16x32_bf16 v[68:71], v[182:185], v[222:225], 0
	v_mfma_f32_16x16x32_bf16 v[64:67], v[190:193], v[222:225], 0
	v_mfma_f32_16x16x32_bf16 v[116:119], v[186:189], v[202:205], v[116:119]
	v_mfma_f32_16x16x32_bf16 v[112:115], v[194:197], v[202:205], v[112:115]
	v_mfma_f32_16x16x32_bf16 v[100:103], v[186:189], v[210:213], v[100:103]
	v_mfma_f32_16x16x32_bf16 v[96:99], v[194:197], v[210:213], v[96:99]
	v_mfma_f32_16x16x32_bf16 v[84:87], v[186:189], v[218:221], v[84:87]
	v_mfma_f32_16x16x32_bf16 v[80:83], v[194:197], v[218:221], v[80:83]
	v_mfma_f32_16x16x32_bf16 v[68:71], v[186:189], v[226:229], v[68:71]
	v_mfma_f32_16x16x32_bf16 v[64:67], v[194:197], v[226:229], v[64:67]
	s_setprio 0
	s_barrier
	ds_read_b128 v[198:201], v150 offset:16384
	ds_read_b128 v[202:205], v150 offset:17408
	ds_read_b128 v[206:209], v150 offset:18432
	ds_read_b128 v[210:213], v150 offset:19456
	ds_read_b128 v[214:217], v150 offset:20480
	ds_read_b128 v[218:221], v150 offset:21504
	ds_read_b128 v[222:225], v150 offset:22528
	ds_read_b128 v[226:229], v150 offset:23552
	v_readfirstlane_b32 s26, v153
	s_mov_b32 s27, m0
	s_mov_b32 m0, s26
	s_nop 0
	global_load_lds_dwordx4 v137, s[34:35]
	s_mov_b32 m0, s27
	v_readfirstlane_b32 s26, v154
	s_mov_b32 s27, m0
	s_mov_b32 m0, s26
	s_nop 0
	global_load_lds_dwordx4 v139, s[34:35]
	s_mov_b32 m0, s27
	s_add_u32 s26, s34, 0x40000
	s_addc_u32 s27, s35, 0
	v_readfirstlane_b32 s52, v155
	s_mov_b32 s53, m0
	s_mov_b32 m0, s52
	s_nop 0
	global_load_lds_dwordx4 v137, s[26:27]
	s_mov_b32 m0, s53
	v_readfirstlane_b32 s52, v156
	s_mov_b32 s53, m0
	s_mov_b32 m0, s52
	s_nop 0
	global_load_lds_dwordx4 v139, s[26:27]
	s_mov_b32 m0, s53
	v_readfirstlane_b32 s26, v157
	s_mov_b32 s27, m0
	s_mov_b32 m0, s26
	s_nop 0
	global_load_lds_dwordx4 v136, s[36:37]
	s_mov_b32 m0, s27
	v_readfirstlane_b32 s26, v158
	s_mov_b32 s27, m0
	s_mov_b32 m0, s26
	s_nop 0
	global_load_lds_dwordx4 v138, s[36:37]
	s_mov_b32 m0, s27
	s_waitcnt vmcnt(8)
	s_waitcnt lgkmcnt(0)
	s_barrier
	s_setprio 1
	s_waitcnt lgkmcnt(7)
	v_mfma_f32_16x16x32_bf16 v[60:63], v[132:135], v[198:201], 0
	v_mfma_f32_16x16x32_bf16 v[56:59], v[174:177], v[198:201], 0
	s_waitcnt lgkmcnt(5)
	v_mfma_f32_16x16x32_bf16 v[44:47], v[132:135], v[206:209], 0
	v_mfma_f32_16x16x32_bf16 v[40:43], v[174:177], v[206:209], 0
	s_waitcnt lgkmcnt(3)
	v_mfma_f32_16x16x32_bf16 v[28:31], v[132:135], v[214:217], 0
	v_mfma_f32_16x16x32_bf16 v[24:27], v[174:177], v[214:217], 0
	s_waitcnt lgkmcnt(1)
	v_mfma_f32_16x16x32_bf16 v[12:15], v[132:135], v[222:225], 0
	v_mfma_f32_16x16x32_bf16 v[8:11], v[174:177], v[222:225], 0
	v_mfma_f32_16x16x32_bf16 v[60:63], v[170:173], v[202:205], v[60:63]
	v_mfma_f32_16x16x32_bf16 v[56:59], v[178:181], v[202:205], v[56:59]
	v_mfma_f32_16x16x32_bf16 v[44:47], v[170:173], v[210:213], v[44:47]
	v_mfma_f32_16x16x32_bf16 v[40:43], v[178:181], v[210:213], v[40:43]
	v_mfma_f32_16x16x32_bf16 v[28:31], v[170:173], v[218:221], v[28:31]
	v_mfma_f32_16x16x32_bf16 v[24:27], v[178:181], v[218:221], v[24:27]
	s_waitcnt lgkmcnt(0)
	v_mfma_f32_16x16x32_bf16 v[12:15], v[170:173], v[226:229], v[12:15]
	v_mfma_f32_16x16x32_bf16 v[8:11], v[178:181], v[226:229], v[8:11]
	s_setprio 0
	s_setprio 1
	v_mfma_f32_16x16x32_bf16 v[52:55], v[182:185], v[198:201], 0
	v_mfma_f32_16x16x32_bf16 v[48:51], v[190:193], v[198:201], 0
	v_mfma_f32_16x16x32_bf16 v[36:39], v[182:185], v[206:209], 0
	v_mfma_f32_16x16x32_bf16 v[32:35], v[190:193], v[206:209], 0
	v_mfma_f32_16x16x32_bf16 v[20:23], v[182:185], v[214:217], 0
	v_mfma_f32_16x16x32_bf16 v[16:19], v[190:193], v[214:217], 0
	v_mfma_f32_16x16x32_bf16 v[4:7], v[182:185], v[222:225], 0
	v_mfma_f32_16x16x32_bf16 v[0:3], v[190:193], v[222:225], 0
	v_mfma_f32_16x16x32_bf16 v[52:55], v[186:189], v[202:205], v[52:55]
	v_mfma_f32_16x16x32_bf16 v[48:51], v[194:197], v[202:205], v[48:51]
	v_mfma_f32_16x16x32_bf16 v[36:39], v[186:189], v[210:213], v[36:39]
	v_mfma_f32_16x16x32_bf16 v[32:35], v[194:197], v[210:213], v[32:35]
	v_mfma_f32_16x16x32_bf16 v[20:23], v[186:189], v[218:221], v[20:23]
	v_mfma_f32_16x16x32_bf16 v[16:19], v[194:197], v[218:221], v[16:19]
	v_mfma_f32_16x16x32_bf16 v[4:7], v[186:189], v[226:229], v[4:7]
	v_mfma_f32_16x16x32_bf16 v[0:3], v[194:197], v[226:229], v[0:3]
	s_setprio 0
	s_barrier
	ds_read_b128 v[132:135], v159
	ds_read_b128 v[170:173], v159 offset:1024
	ds_read_b128 v[174:177], v159 offset:2048
	ds_read_b128 v[178:181], v159 offset:3072
	ds_read_b128 v[182:185], v160
	ds_read_b128 v[186:189], v160 offset:1024
	ds_read_b128 v[190:193], v160 offset:2048
	ds_read_b128 v[194:197], v160 offset:3072
	ds_read_b128 v[198:201], v150 offset:32768
	ds_read_b128 v[202:205], v150 offset:33792
	ds_read_b128 v[206:209], v150 offset:34816
	ds_read_b128 v[210:213], v150 offset:35840
	ds_read_b128 v[214:217], v150 offset:36864
	ds_read_b128 v[218:221], v150 offset:37888
	ds_read_b128 v[222:225], v150 offset:38912
	ds_read_b128 v[226:229], v150 offset:39936
	s_add_u32 s26, s36, 0x40000
	s_addc_u32 s27, s37, 0
	v_readfirstlane_b32 s36, v161
	s_mov_b32 s37, m0
	s_mov_b32 m0, s36
	s_nop 0
	global_load_lds_dwordx4 v136, s[26:27]
	s_mov_b32 m0, s37
	v_readfirstlane_b32 s36, v162
	s_mov_b32 s37, m0
	s_mov_b32 m0, s36
	s_nop 0
	global_load_lds_dwordx4 v138, s[26:27]
	s_mov_b32 m0, s37
	s_waitcnt vmcnt(8)
	s_waitcnt lgkmcnt(0)
	s_barrier
	s_setprio 1
	s_waitcnt lgkmcnt(7)
	v_mfma_f32_16x16x32_bf16 v[124:127], v[132:135], v[198:201], v[124:127]
	v_mfma_f32_16x16x32_bf16 v[120:123], v[174:177], v[198:201], v[120:123]
	s_waitcnt lgkmcnt(5)
	v_mfma_f32_16x16x32_bf16 v[108:111], v[132:135], v[206:209], v[108:111]
	v_mfma_f32_16x16x32_bf16 v[104:107], v[174:177], v[206:209], v[104:107]
	s_waitcnt lgkmcnt(3)
	v_mfma_f32_16x16x32_bf16 v[92:95], v[132:135], v[214:217], v[92:95]
	v_mfma_f32_16x16x32_bf16 v[88:91], v[174:177], v[214:217], v[88:91]
	s_waitcnt lgkmcnt(1)
	v_mfma_f32_16x16x32_bf16 v[76:79], v[132:135], v[222:225], v[76:79]
	v_mfma_f32_16x16x32_bf16 v[72:75], v[174:177], v[222:225], v[72:75]
	v_mfma_f32_16x16x32_bf16 v[124:127], v[170:173], v[202:205], v[124:127]
	v_mfma_f32_16x16x32_bf16 v[120:123], v[178:181], v[202:205], v[120:123]
	v_mfma_f32_16x16x32_bf16 v[108:111], v[170:173], v[210:213], v[108:111]
	v_mfma_f32_16x16x32_bf16 v[104:107], v[178:181], v[210:213], v[104:107]
	v_mfma_f32_16x16x32_bf16 v[92:95], v[170:173], v[218:221], v[92:95]
	v_mfma_f32_16x16x32_bf16 v[88:91], v[178:181], v[218:221], v[88:91]
	s_waitcnt lgkmcnt(0)
	v_mfma_f32_16x16x32_bf16 v[76:79], v[170:173], v[226:229], v[76:79]
	v_mfma_f32_16x16x32_bf16 v[72:75], v[178:181], v[226:229], v[72:75]
	s_setprio 0
	s_setprio 1
	v_mfma_f32_16x16x32_bf16 v[116:119], v[182:185], v[198:201], v[116:119]
	v_mfma_f32_16x16x32_bf16 v[112:115], v[190:193], v[198:201], v[112:115]
	v_mfma_f32_16x16x32_bf16 v[100:103], v[182:185], v[206:209], v[100:103]
	v_mfma_f32_16x16x32_bf16 v[96:99], v[190:193], v[206:209], v[96:99]
	v_mfma_f32_16x16x32_bf16 v[84:87], v[182:185], v[214:217], v[84:87]
	v_mfma_f32_16x16x32_bf16 v[80:83], v[190:193], v[214:217], v[80:83]
	v_mfma_f32_16x16x32_bf16 v[68:71], v[182:185], v[222:225], v[68:71]
	v_mfma_f32_16x16x32_bf16 v[64:67], v[190:193], v[222:225], v[64:67]
	v_mfma_f32_16x16x32_bf16 v[116:119], v[186:189], v[202:205], v[116:119]
	v_mfma_f32_16x16x32_bf16 v[112:115], v[194:197], v[202:205], v[112:115]
	v_mfma_f32_16x16x32_bf16 v[100:103], v[186:189], v[210:213], v[100:103]
	v_mfma_f32_16x16x32_bf16 v[96:99], v[194:197], v[210:213], v[96:99]
	v_mfma_f32_16x16x32_bf16 v[84:87], v[186:189], v[218:221], v[84:87]
	v_mfma_f32_16x16x32_bf16 v[80:83], v[194:197], v[218:221], v[80:83]
	v_mfma_f32_16x16x32_bf16 v[68:71], v[186:189], v[226:229], v[68:71]
	v_mfma_f32_16x16x32_bf16 v[64:67], v[194:197], v[226:229], v[64:67]
	s_setprio 0
	s_barrier
	ds_read_b128 v[198:201], v150 offset:49152
	ds_read_b128 v[202:205], v150 offset:50176
	ds_read_b128 v[206:209], v150 offset:51200
	ds_read_b128 v[210:213], v150 offset:52224
	ds_read_b128 v[214:217], v150 offset:53248
	ds_read_b128 v[218:221], v150 offset:54272
	ds_read_b128 v[222:225], v150 offset:55296
	ds_read_b128 v[226:229], v150 offset:56320
	s_add_u32 s26, s34, 0x80
	s_addc_u32 s27, s35, 0
	v_readfirstlane_b32 s36, v141
	s_mov_b32 s37, m0
	s_mov_b32 m0, s36
	s_nop 0
	global_load_lds_dwordx4 v137, s[26:27]
	s_mov_b32 m0, s37
	v_readfirstlane_b32 s36, v142
	s_mov_b32 s37, m0
	s_mov_b32 m0, s36
	s_nop 0
	global_load_lds_dwordx4 v139, s[26:27]
	s_mov_b32 m0, s37
	s_add_u32 s26, s34, 0x40080
	s_addc_u32 s27, s35, 0
	v_readfirstlane_b32 s34, v145
	s_mov_b32 s35, m0
	s_mov_b32 m0, s34
	s_nop 0
	global_load_lds_dwordx4 v137, s[26:27]
	s_mov_b32 m0, s35
	v_readfirstlane_b32 s34, v146
	s_mov_b32 s35, m0
	s_mov_b32 m0, s34
	s_nop 0
	global_load_lds_dwordx4 v139, s[26:27]
	s_mov_b32 m0, s35
	v_readfirstlane_b32 s26, v143
	s_mov_b32 s27, m0
	s_mov_b32 m0, s26
	s_nop 0
	global_load_lds_dwordx4 v136, s[30:31]
	s_mov_b32 m0, s27
	v_readfirstlane_b32 s26, v144
	s_mov_b32 s27, m0
	s_mov_b32 m0, s26
	s_nop 0
	global_load_lds_dwordx4 v138, s[30:31]
	s_mov_b32 m0, s27
	s_waitcnt vmcnt(8)
	s_waitcnt lgkmcnt(0)
	s_barrier
	s_setprio 1
	s_waitcnt lgkmcnt(7)
	v_mfma_f32_16x16x32_bf16 v[60:63], v[132:135], v[198:201], v[60:63]
	v_mfma_f32_16x16x32_bf16 v[56:59], v[174:177], v[198:201], v[56:59]
	s_waitcnt lgkmcnt(5)
	v_mfma_f32_16x16x32_bf16 v[44:47], v[132:135], v[206:209], v[44:47]
	v_mfma_f32_16x16x32_bf16 v[40:43], v[174:177], v[206:209], v[40:43]
	s_waitcnt lgkmcnt(3)
	v_mfma_f32_16x16x32_bf16 v[28:31], v[132:135], v[214:217], v[28:31]
	v_mfma_f32_16x16x32_bf16 v[24:27], v[174:177], v[214:217], v[24:27]
	s_waitcnt lgkmcnt(1)
	v_mfma_f32_16x16x32_bf16 v[12:15], v[132:135], v[222:225], v[12:15]
	v_mfma_f32_16x16x32_bf16 v[8:11], v[174:177], v[222:225], v[8:11]
	v_mfma_f32_16x16x32_bf16 v[60:63], v[170:173], v[202:205], v[60:63]
	v_mfma_f32_16x16x32_bf16 v[56:59], v[178:181], v[202:205], v[56:59]
	v_mfma_f32_16x16x32_bf16 v[44:47], v[170:173], v[210:213], v[44:47]
	v_mfma_f32_16x16x32_bf16 v[40:43], v[178:181], v[210:213], v[40:43]
	v_mfma_f32_16x16x32_bf16 v[28:31], v[170:173], v[218:221], v[28:31]
	v_mfma_f32_16x16x32_bf16 v[24:27], v[178:181], v[218:221], v[24:27]
	s_waitcnt lgkmcnt(0)
	v_mfma_f32_16x16x32_bf16 v[12:15], v[170:173], v[226:229], v[12:15]
	v_mfma_f32_16x16x32_bf16 v[8:11], v[178:181], v[226:229], v[8:11]
	s_setprio 0
	s_setprio 1
	v_mfma_f32_16x16x32_bf16 v[52:55], v[182:185], v[198:201], v[52:55]
	v_mfma_f32_16x16x32_bf16 v[48:51], v[190:193], v[198:201], v[48:51]
	v_mfma_f32_16x16x32_bf16 v[36:39], v[182:185], v[206:209], v[36:39]
	v_mfma_f32_16x16x32_bf16 v[32:35], v[190:193], v[206:209], v[32:35]
	v_mfma_f32_16x16x32_bf16 v[20:23], v[182:185], v[214:217], v[20:23]
	v_mfma_f32_16x16x32_bf16 v[16:19], v[190:193], v[214:217], v[16:19]
	v_mfma_f32_16x16x32_bf16 v[4:7], v[182:185], v[222:225], v[4:7]
	v_mfma_f32_16x16x32_bf16 v[0:3], v[190:193], v[222:225], v[0:3]
	v_mfma_f32_16x16x32_bf16 v[52:55], v[186:189], v[202:205], v[52:55]
	v_mfma_f32_16x16x32_bf16 v[48:51], v[194:197], v[202:205], v[48:51]
	v_mfma_f32_16x16x32_bf16 v[36:39], v[186:189], v[210:213], v[36:39]
	v_mfma_f32_16x16x32_bf16 v[32:35], v[194:197], v[210:213], v[32:35]
	v_mfma_f32_16x16x32_bf16 v[20:23], v[186:189], v[218:221], v[20:23]
	v_mfma_f32_16x16x32_bf16 v[16:19], v[194:197], v[218:221], v[16:19]
	v_mfma_f32_16x16x32_bf16 v[4:7], v[186:189], v[226:229], v[4:7]
	v_mfma_f32_16x16x32_bf16 v[0:3], v[194:197], v[226:229], v[0:3]
	s_setprio 0
	s_barrier
	s_add_i32 s51, s51, 2
	s_add_u32 s45, s45, 0x100
	s_addc_u32 s50, s50, 0
	s_cmp_gt_u32 s51, 13
	s_mov_b64 s[26:27], s[28:29]
	s_branch .LBB0_569

.LBB0_663:
	s_ashr_i32 s13, s12, 31
	s_lshl_b64 s[16:17], s[12:13], 19
	s_add_u32 s18, s60, s16
	s_addc_u32 s19, s61, s17
	s_and_b64 s[16:17], s[36:37], exec
	s_cselect_b32 s13, s19, s15
	s_cselect_b32 s78, s18, s14
	s_ashr_i32 s11, s10, 31
	s_lshl_b64 s[16:17], s[10:11], 19
	s_add_u32 s16, s3, s16
	s_addc_u32 s17, s26, s17
	s_and_b64 s[22:23], s[36:37], exec
	s_cselect_b32 s11, s17, s21
	s_cselect_b32 s79, s16, s20
	s_add_u32 s80, s20, 0x100
	s_addc_u32 s81, s21, 0
	s_mov_b32 s86, -2
	ds_read_b128 v[142:145], v155
	ds_read_b128 v[160:163], v155 offset:1024
	ds_read_b128 v[166:169], v155 offset:2048
	ds_read_b128 v[170:173], v155 offset:3072
	ds_read_b128 v[174:177], v156
	ds_read_b128 v[178:181], v156 offset:1024
	ds_read_b128 v[182:185], v156 offset:2048
	ds_read_b128 v[186:189], v156 offset:3072
	s_add_u32 vcc_lo, s14, 0x100
	s_addc_u32 vcc_hi, s15, 0
	s_cmp_eq_u32 s86, 12
	s_cselect_b32 s24, s78, vcc_lo
	s_cselect_b32 s25, s13, vcc_hi
	s_cselect_b32 s22, s79, s80
	s_cselect_b32 s23, s11, s81
	s_add_u32 s20, s24, 0x80
	s_addc_u32 s21, s25, 0
	ds_read_b128 v[190:193], v157
	ds_read_b128 v[194:197], v157 offset:1024
	ds_read_b128 v[198:201], v157 offset:2048
	ds_read_b128 v[202:205], v157 offset:3072
	ds_read_b128 v[206:209], v157 offset:4096
	ds_read_b128 v[210:213], v157 offset:5120
	ds_read_b128 v[214:217], v157 offset:6144
	ds_read_b128 v[218:221], v157 offset:7168
	s_add_u32 s14, s14, 0x40080
	s_addc_u32 s15, s15, 0
	s_mov_b32 s87, m0
	s_mov_b32 m0, s82
	s_nop 0
	global_load_lds_dwordx4 v150, s[14:15]
	s_mov_b32 m0, s87
	s_add_i32 s87, s30, 0xe000
	s_mov_b32 s90, m0
	s_mov_b32 m0, s87
	s_nop 0
	global_load_lds_dwordx4 v152, s[14:15]
	s_mov_b32 m0, s90
	s_waitcnt vmcnt(8)
	s_waitcnt lgkmcnt(0)
	s_barrier
	s_setprio 1
	s_waitcnt lgkmcnt(7)
	v_mfma_f32_16x16x32_bf16 v[124:127], v[142:145], v[190:193], 0
	v_mfma_f32_16x16x32_bf16 v[120:123], v[166:169], v[190:193], 0
	s_waitcnt lgkmcnt(5)
	v_mfma_f32_16x16x32_bf16 v[108:111], v[142:145], v[198:201], 0
	v_mfma_f32_16x16x32_bf16 v[104:107], v[166:169], v[198:201], 0
	s_waitcnt lgkmcnt(3)
	v_mfma_f32_16x16x32_bf16 v[92:95], v[142:145], v[206:209], 0
	v_mfma_f32_16x16x32_bf16 v[88:91], v[166:169], v[206:209], 0
	s_waitcnt lgkmcnt(1)
	v_mfma_f32_16x16x32_bf16 v[76:79], v[142:145], v[214:217], 0
	v_mfma_f32_16x16x32_bf16 v[72:75], v[166:169], v[214:217], 0
	v_mfma_f32_16x16x32_bf16 v[124:127], v[160:163], v[194:197], v[124:127]
	v_mfma_f32_16x16x32_bf16 v[120:123], v[170:173], v[194:197], v[120:123]
	v_mfma_f32_16x16x32_bf16 v[108:111], v[160:163], v[202:205], v[108:111]
	v_mfma_f32_16x16x32_bf16 v[104:107], v[170:173], v[202:205], v[104:107]
	v_mfma_f32_16x16x32_bf16 v[92:95], v[160:163], v[210:213], v[92:95]
	v_mfma_f32_16x16x32_bf16 v[88:91], v[170:173], v[210:213], v[88:91]
	s_waitcnt lgkmcnt(0)
	v_mfma_f32_16x16x32_bf16 v[76:79], v[160:163], v[218:221], v[76:79]
	v_mfma_f32_16x16x32_bf16 v[72:75], v[170:173], v[218:221], v[72:75]
	s_setprio 0
	s_setprio 1
	v_mfma_f32_16x16x32_bf16 v[116:119], v[174:177], v[190:193], 0
	v_mfma_f32_16x16x32_bf16 v[112:115], v[182:185], v[190:193], 0
	v_mfma_f32_16x16x32_bf16 v[100:103], v[174:177], v[198:201], 0
	v_mfma_f32_16x16x32_bf16 v[96:99], v[182:185], v[198:201], 0
	v_mfma_f32_16x16x32_bf16 v[84:87], v[174:177], v[206:209], 0
	v_mfma_f32_16x16x32_bf16 v[80:83], v[182:185], v[206:209], 0
	v_mfma_f32_16x16x32_bf16 v[68:71], v[174:177], v[214:217], 0
	v_mfma_f32_16x16x32_bf16 v[64:67], v[182:185], v[214:217], 0
	v_mfma_f32_16x16x32_bf16 v[116:119], v[178:181], v[194:197], v[116:119]
	v_mfma_f32_16x16x32_bf16 v[112:115], v[186:189], v[194:197], v[112:115]
	v_mfma_f32_16x16x32_bf16 v[100:103], v[178:181], v[202:205], v[100:103]
	v_mfma_f32_16x16x32_bf16 v[96:99], v[186:189], v[202:205], v[96:99]
	v_mfma_f32_16x16x32_bf16 v[84:87], v[178:181], v[210:213], v[84:87]
	v_mfma_f32_16x16x32_bf16 v[80:83], v[186:189], v[210:213], v[80:83]
	v_mfma_f32_16x16x32_bf16 v[68:71], v[178:181], v[218:221], v[68:71]
	v_mfma_f32_16x16x32_bf16 v[64:67], v[186:189], v[218:221], v[64:67]
	s_setprio 0
	s_barrier
	ds_read_b128 v[190:193], v157 offset:16384
	ds_read_b128 v[194:197], v157 offset:17408
	ds_read_b128 v[198:201], v157 offset:18432
	ds_read_b128 v[202:205], v157 offset:19456
	ds_read_b128 v[206:209], v157 offset:20480
	ds_read_b128 v[210:213], v157 offset:21504
	ds_read_b128 v[214:217], v157 offset:22528
	ds_read_b128 v[218:221], v157 offset:23552
	s_mov_b32 s14, m0
	s_mov_b32 m0, s31
	s_nop 0
	global_load_lds_dwordx4 v151, s[22:23]
	s_mov_b32 m0, s14
	s_nop 0
	s_mov_b32 s14, m0
	s_mov_b32 m0, s34
	s_nop 0
	global_load_lds_dwordx4 v153, s[22:23]
	s_mov_b32 m0, s14
	s_add_u32 s14, s22, 0x40000
	s_addc_u32 s15, s23, 0
	s_mov_b32 s87, m0
	s_mov_b32 m0, s35
	s_nop 0
	global_load_lds_dwordx4 v151, s[14:15]
	s_mov_b32 m0, s87
	s_nop 0
	s_mov_b32 s87, m0
	s_mov_b32 m0, s38
	s_nop 0
	global_load_lds_dwordx4 v153, s[14:15]
	s_mov_b32 m0, s87
	s_mov_b32 s14, m0
	s_mov_b32 m0, s30
	s_nop 0
	global_load_lds_dwordx4 v150, s[24:25]
	s_mov_b32 m0, s14
	s_nop 0
	s_mov_b32 s14, m0
	s_mov_b32 m0, s39
	s_nop 0
	global_load_lds_dwordx4 v152, s[24:25]
	s_mov_b32 m0, s14
	s_waitcnt vmcnt(8)
	s_waitcnt lgkmcnt(0)
	s_barrier
	s_setprio 1
	s_waitcnt lgkmcnt(7)
	v_mfma_f32_16x16x32_bf16 v[60:63], v[142:145], v[190:193], 0
	v_mfma_f32_16x16x32_bf16 v[56:59], v[166:169], v[190:193], 0
	s_waitcnt lgkmcnt(5)
	v_mfma_f32_16x16x32_bf16 v[44:47], v[142:145], v[198:201], 0
	v_mfma_f32_16x16x32_bf16 v[40:43], v[166:169], v[198:201], 0
	s_waitcnt lgkmcnt(3)
	v_mfma_f32_16x16x32_bf16 v[28:31], v[142:145], v[206:209], 0
	v_mfma_f32_16x16x32_bf16 v[24:27], v[166:169], v[206:209], 0
	s_waitcnt lgkmcnt(1)
	v_mfma_f32_16x16x32_bf16 v[12:15], v[142:145], v[214:217], 0
	v_mfma_f32_16x16x32_bf16 v[8:11], v[166:169], v[214:217], 0
	v_mfma_f32_16x16x32_bf16 v[60:63], v[160:163], v[194:197], v[60:63]
	v_mfma_f32_16x16x32_bf16 v[56:59], v[170:173], v[194:197], v[56:59]
	v_mfma_f32_16x16x32_bf16 v[44:47], v[160:163], v[202:205], v[44:47]
	v_mfma_f32_16x16x32_bf16 v[40:43], v[170:173], v[202:205], v[40:43]
	v_mfma_f32_16x16x32_bf16 v[28:31], v[160:163], v[210:213], v[28:31]
	v_mfma_f32_16x16x32_bf16 v[24:27], v[170:173], v[210:213], v[24:27]
	s_waitcnt lgkmcnt(0)
	v_mfma_f32_16x16x32_bf16 v[12:15], v[160:163], v[218:221], v[12:15]
	v_mfma_f32_16x16x32_bf16 v[8:11], v[170:173], v[218:221], v[8:11]
	s_setprio 0
	s_setprio 1
	v_mfma_f32_16x16x32_bf16 v[52:55], v[174:177], v[190:193], 0
	v_mfma_f32_16x16x32_bf16 v[48:51], v[182:185], v[190:193], 0
	v_mfma_f32_16x16x32_bf16 v[36:39], v[174:177], v[198:201], 0
	v_mfma_f32_16x16x32_bf16 v[32:35], v[182:185], v[198:201], 0
	v_mfma_f32_16x16x32_bf16 v[20:23], v[174:177], v[206:209], 0
	v_mfma_f32_16x16x32_bf16 v[16:19], v[182:185], v[206:209], 0
	v_mfma_f32_16x16x32_bf16 v[4:7], v[174:177], v[214:217], 0
	v_mfma_f32_16x16x32_bf16 v[0:3], v[182:185], v[214:217], 0
	v_mfma_f32_16x16x32_bf16 v[52:55], v[178:181], v[194:197], v[52:55]
	v_mfma_f32_16x16x32_bf16 v[48:51], v[186:189], v[194:197], v[48:51]
	v_mfma_f32_16x16x32_bf16 v[36:39], v[178:181], v[202:205], v[36:39]
	v_mfma_f32_16x16x32_bf16 v[32:35], v[186:189], v[202:205], v[32:35]
	v_mfma_f32_16x16x32_bf16 v[20:23], v[178:181], v[210:213], v[20:23]
	v_mfma_f32_16x16x32_bf16 v[16:19], v[186:189], v[210:213], v[16:19]
	v_mfma_f32_16x16x32_bf16 v[4:7], v[178:181], v[218:221], v[4:7]
	v_mfma_f32_16x16x32_bf16 v[0:3], v[186:189], v[218:221], v[0:3]
	s_setprio 0
	s_barrier
	ds_read_b128 v[142:145], v158
	ds_read_b128 v[160:163], v158 offset:1024
	ds_read_b128 v[166:169], v158 offset:2048
	ds_read_b128 v[170:173], v158 offset:3072
	ds_read_b128 v[174:177], v159
	ds_read_b128 v[178:181], v159 offset:1024
	ds_read_b128 v[182:185], v159 offset:2048
	ds_read_b128 v[186:189], v159 offset:3072
	ds_read_b128 v[190:193], v157 offset:32768
	ds_read_b128 v[194:197], v157 offset:33792
	ds_read_b128 v[198:201], v157 offset:34816
	ds_read_b128 v[202:205], v157 offset:35840
	ds_read_b128 v[206:209], v157 offset:36864
	ds_read_b128 v[210:213], v157 offset:37888
	ds_read_b128 v[214:217], v157 offset:38912
	ds_read_b128 v[218:221], v157 offset:39936
	s_add_u32 s14, s24, 0x40000
	s_addc_u32 s15, s25, 0
	s_mov_b32 s24, m0
	s_mov_b32 m0, s40
	s_nop 0
	global_load_lds_dwordx4 v150, s[14:15]
	s_mov_b32 m0, s24
	s_nop 0
	s_mov_b32 s24, m0
	s_mov_b32 m0, s41
	s_nop 0
	global_load_lds_dwordx4 v152, s[14:15]
	s_mov_b32 m0, s24
	s_waitcnt vmcnt(8)
	s_waitcnt lgkmcnt(0)
	s_barrier
	s_setprio 1
	s_waitcnt lgkmcnt(7)
	v_mfma_f32_16x16x32_bf16 v[124:127], v[142:145], v[190:193], v[124:127]
	v_mfma_f32_16x16x32_bf16 v[120:123], v[166:169], v[190:193], v[120:123]
	s_waitcnt lgkmcnt(5)
	v_mfma_f32_16x16x32_bf16 v[108:111], v[142:145], v[198:201], v[108:111]
	v_mfma_f32_16x16x32_bf16 v[104:107], v[166:169], v[198:201], v[104:107]
	s_waitcnt lgkmcnt(3)
	v_mfma_f32_16x16x32_bf16 v[92:95], v[142:145], v[206:209], v[92:95]
	v_mfma_f32_16x16x32_bf16 v[88:91], v[166:169], v[206:209], v[88:91]
	s_waitcnt lgkmcnt(1)
	v_mfma_f32_16x16x32_bf16 v[76:79], v[142:145], v[214:217], v[76:79]
	v_mfma_f32_16x16x32_bf16 v[72:75], v[166:169], v[214:217], v[72:75]
	v_mfma_f32_16x16x32_bf16 v[124:127], v[160:163], v[194:197], v[124:127]
	v_mfma_f32_16x16x32_bf16 v[120:123], v[170:173], v[194:197], v[120:123]
	v_mfma_f32_16x16x32_bf16 v[108:111], v[160:163], v[202:205], v[108:111]
	v_mfma_f32_16x16x32_bf16 v[104:107], v[170:173], v[202:205], v[104:107]
	v_mfma_f32_16x16x32_bf16 v[92:95], v[160:163], v[210:213], v[92:95]
	v_mfma_f32_16x16x32_bf16 v[88:91], v[170:173], v[210:213], v[88:91]
	s_waitcnt lgkmcnt(0)
	v_mfma_f32_16x16x32_bf16 v[76:79], v[160:163], v[218:221], v[76:79]
	v_mfma_f32_16x16x32_bf16 v[72:75], v[170:173], v[218:221], v[72:75]
	s_setprio 0
	s_setprio 1
	v_mfma_f32_16x16x32_bf16 v[116:119], v[174:177], v[190:193], v[116:119]
	v_mfma_f32_16x16x32_bf16 v[112:115], v[182:185], v[190:193], v[112:115]
	v_mfma_f32_16x16x32_bf16 v[100:103], v[174:177], v[198:201], v[100:103]
	v_mfma_f32_16x16x32_bf16 v[96:99], v[182:185], v[198:201], v[96:99]
	v_mfma_f32_16x16x32_bf16 v[84:87], v[174:177], v[206:209], v[84:87]
	v_mfma_f32_16x16x32_bf16 v[80:83], v[182:185], v[206:209], v[80:83]
	v_mfma_f32_16x16x32_bf16 v[68:71], v[174:177], v[214:217], v[68:71]
	v_mfma_f32_16x16x32_bf16 v[64:67], v[182:185], v[214:217], v[64:67]
	v_mfma_f32_16x16x32_bf16 v[116:119], v[178:181], v[194:197], v[116:119]
	v_mfma_f32_16x16x32_bf16 v[112:115], v[186:189], v[194:197], v[112:115]
	v_mfma_f32_16x16x32_bf16 v[100:103], v[178:181], v[202:205], v[100:103]
	v_mfma_f32_16x16x32_bf16 v[96:99], v[186:189], v[202:205], v[96:99]
	v_mfma_f32_16x16x32_bf16 v[84:87], v[178:181], v[210:213], v[84:87]
	v_mfma_f32_16x16x32_bf16 v[80:83], v[186:189], v[210:213], v[80:83]
	v_mfma_f32_16x16x32_bf16 v[68:71], v[178:181], v[218:221], v[68:71]
	v_mfma_f32_16x16x32_bf16 v[64:67], v[186:189], v[218:221], v[64:67]
	s_setprio 0
	s_barrier
	ds_read_b128 v[190:193], v157 offset:49152
	ds_read_b128 v[194:197], v157 offset:50176
	ds_read_b128 v[198:201], v157 offset:51200
	ds_read_b128 v[202:205], v157 offset:52224
	ds_read_b128 v[206:209], v157 offset:53248
	ds_read_b128 v[210:213], v157 offset:54272
	ds_read_b128 v[214:217], v157 offset:55296
	ds_read_b128 v[218:221], v157 offset:56320
	s_add_u32 s14, s22, 0x80
	s_addc_u32 s15, s23, 0
	s_mov_b32 s24, m0
	s_mov_b32 m0, s44
	s_nop 0
	global_load_lds_dwordx4 v151, s[14:15]
	s_mov_b32 m0, s24
	s_nop 0
	s_mov_b32 s24, m0
	s_mov_b32 m0, s45
	s_nop 0
	global_load_lds_dwordx4 v153, s[14:15]
	s_mov_b32 m0, s24
	s_add_u32 s14, s22, 0x40080
	s_addc_u32 s15, s23, 0
	s_mov_b32 s22, m0
	s_mov_b32 m0, s66
	s_nop 0
	global_load_lds_dwordx4 v151, s[14:15]
	s_mov_b32 m0, s22
	s_nop 0
	s_mov_b32 s22, m0
	s_mov_b32 m0, s67
	s_nop 0
	global_load_lds_dwordx4 v153, s[14:15]
	s_mov_b32 m0, s22
	s_mov_b32 s14, m0
	s_mov_b32 m0, s64
	s_nop 0
	global_load_lds_dwordx4 v150, s[20:21]
	s_mov_b32 m0, s14
	s_nop 0
	s_mov_b32 s14, m0
	s_mov_b32 m0, s65
	s_nop 0
	global_load_lds_dwordx4 v152, s[20:21]
	s_mov_b32 m0, s14
	s_waitcnt vmcnt(8)
	s_waitcnt lgkmcnt(0)
	s_barrier
	s_setprio 1
	s_waitcnt lgkmcnt(7)
	v_mfma_f32_16x16x32_bf16 v[60:63], v[142:145], v[190:193], v[60:63]
	v_mfma_f32_16x16x32_bf16 v[56:59], v[166:169], v[190:193], v[56:59]
	s_waitcnt lgkmcnt(5)
	v_mfma_f32_16x16x32_bf16 v[44:47], v[142:145], v[198:201], v[44:47]
	v_mfma_f32_16x16x32_bf16 v[40:43], v[166:169], v[198:201], v[40:43]
	s_waitcnt lgkmcnt(3)
	v_mfma_f32_16x16x32_bf16 v[28:31], v[142:145], v[206:209], v[28:31]
	v_mfma_f32_16x16x32_bf16 v[24:27], v[166:169], v[206:209], v[24:27]
	s_waitcnt lgkmcnt(1)
	v_mfma_f32_16x16x32_bf16 v[12:15], v[142:145], v[214:217], v[12:15]
	v_mfma_f32_16x16x32_bf16 v[8:11], v[166:169], v[214:217], v[8:11]
	v_mfma_f32_16x16x32_bf16 v[60:63], v[160:163], v[194:197], v[60:63]
	v_mfma_f32_16x16x32_bf16 v[56:59], v[170:173], v[194:197], v[56:59]
	v_mfma_f32_16x16x32_bf16 v[44:47], v[160:163], v[202:205], v[44:47]
	v_mfma_f32_16x16x32_bf16 v[40:43], v[170:173], v[202:205], v[40:43]
	v_mfma_f32_16x16x32_bf16 v[28:31], v[160:163], v[210:213], v[28:31]
	v_mfma_f32_16x16x32_bf16 v[24:27], v[170:173], v[210:213], v[24:27]
	s_waitcnt lgkmcnt(0)
	v_mfma_f32_16x16x32_bf16 v[12:15], v[160:163], v[218:221], v[12:15]
	v_mfma_f32_16x16x32_bf16 v[8:11], v[170:173], v[218:221], v[8:11]
	s_setprio 0
	s_setprio 1
	v_mfma_f32_16x16x32_bf16 v[52:55], v[174:177], v[190:193], v[52:55]
	v_mfma_f32_16x16x32_bf16 v[48:51], v[182:185], v[190:193], v[48:51]
	v_mfma_f32_16x16x32_bf16 v[36:39], v[174:177], v[198:201], v[36:39]
	v_mfma_f32_16x16x32_bf16 v[32:35], v[182:185], v[198:201], v[32:35]
	v_mfma_f32_16x16x32_bf16 v[20:23], v[174:177], v[206:209], v[20:23]
	v_mfma_f32_16x16x32_bf16 v[16:19], v[182:185], v[206:209], v[16:19]
	v_mfma_f32_16x16x32_bf16 v[4:7], v[174:177], v[214:217], v[4:7]
	v_mfma_f32_16x16x32_bf16 v[0:3], v[182:185], v[214:217], v[0:3]
	v_mfma_f32_16x16x32_bf16 v[52:55], v[178:181], v[194:197], v[52:55]
	v_mfma_f32_16x16x32_bf16 v[48:51], v[186:189], v[194:197], v[48:51]
	v_mfma_f32_16x16x32_bf16 v[36:39], v[178:181], v[202:205], v[36:39]
	v_mfma_f32_16x16x32_bf16 v[32:35], v[186:189], v[202:205], v[32:35]
	v_mfma_f32_16x16x32_bf16 v[20:23], v[178:181], v[210:213], v[20:23]
	v_mfma_f32_16x16x32_bf16 v[16:19], v[186:189], v[210:213], v[16:19]
	v_mfma_f32_16x16x32_bf16 v[4:7], v[178:181], v[218:221], v[4:7]
	v_mfma_f32_16x16x32_bf16 v[0:3], v[186:189], v[218:221], v[0:3]
	s_setprio 0
	s_barrier
	s_add_i32 s86, s86, 2
	s_add_u32 s80, s80, 0x100
	s_addc_u32 s81, s81, 0
	s_cmp_gt_u32 s86, 13
	s_mov_b64 s[14:15], vcc
	s_branch .LBB0_664

.LBB0_732:
	s_ashr_i32 s11, s10, 31
	s_lshl_b64 s[12:13], s[10:11], 21
	s_add_u32 s12, s48, s12
	s_addc_u32 s13, s49, s13
	s_and_b64 s[14:15], s[36:37], exec
	s_cselect_b32 s11, s13, s17
	s_cselect_b32 vcc_lo, s12, s16
	s_ashr_i32 s9, s8, 31
	s_lshl_b64 s[14:15], s[8:9], 21
	s_add_u32 s14, s33, s14
	s_addc_u32 s15, s28, s15
	s_and_b64 s[20:21], s[36:37], exec
	s_cselect_b32 s9, s15, s19
	s_cselect_b32 s78, s14, s18
	s_add_u32 s79, s18, 0x100
	s_addc_u32 vcc_hi, s19, 0
	s_mov_b32 s80, -2
	v_add_u32_e32 v155, 0x10000, v153
	ds_read_b128 v[142:145], v155
	ds_read_b128 v[156:159], v155 offset:1024
	ds_read_b128 v[160:163], v155 offset:2048
	ds_read_b128 v[166:169], v155 offset:3072
	v_add_u32_e32 v155, 0x14000, v153
	ds_read_b128 v[170:173], v155
	ds_read_b128 v[174:177], v155 offset:1024
	ds_read_b128 v[178:181], v155 offset:2048
	ds_read_b128 v[182:185], v155 offset:3072
	s_add_u32 s18, s16, 0x100
	s_addc_u32 s19, s17, 0
	s_cmp_eq_u32 s80, 60
	s_cselect_b32 s24, vcc_lo, s18
	s_cselect_b32 s25, s11, s19
	s_cselect_b32 s22, s78, s79
	s_cselect_b32 s23, s9, vcc_hi
	s_add_u32 s20, s24, 0x80
	s_addc_u32 s21, s25, 0
	ds_read_b128 v[186:189], v154
	ds_read_b128 v[190:193], v154 offset:1024
	ds_read_b128 v[194:197], v154 offset:2048
	ds_read_b128 v[198:201], v154 offset:3072
	ds_read_b128 v[202:205], v154 offset:4096
	ds_read_b128 v[206:209], v154 offset:5120
	ds_read_b128 v[210:213], v154 offset:6144
	ds_read_b128 v[214:217], v154 offset:7168
	s_add_u32 s16, s16, 0x100080
	s_addc_u32 s17, s17, 0
	s_mov_b32 s81, m0
	s_mov_b32 m0, s83
	s_nop 0
	global_load_lds_dwordx4 v132, s[16:17]
	s_mov_b32 m0, s81
	s_add_i32 s81, s38, 0xe000
	s_mov_b32 s86, m0
	s_mov_b32 m0, s81
	s_nop 0
	global_load_lds_dwordx4 v147, s[16:17]
	s_mov_b32 m0, s86
	s_waitcnt vmcnt(8)
	s_waitcnt lgkmcnt(0)
	s_barrier
	s_setprio 1
	s_waitcnt lgkmcnt(7)
	v_mfma_f32_16x16x32_bf16 v[124:127], v[142:145], v[186:189], 0
	v_mfma_f32_16x16x32_bf16 v[120:123], v[160:163], v[186:189], 0
	s_waitcnt lgkmcnt(5)
	v_mfma_f32_16x16x32_bf16 v[108:111], v[142:145], v[194:197], 0
	v_mfma_f32_16x16x32_bf16 v[104:107], v[160:163], v[194:197], 0
	s_waitcnt lgkmcnt(3)
	v_mfma_f32_16x16x32_bf16 v[92:95], v[142:145], v[202:205], 0
	v_mfma_f32_16x16x32_bf16 v[88:91], v[160:163], v[202:205], 0
	s_waitcnt lgkmcnt(1)
	v_mfma_f32_16x16x32_bf16 v[76:79], v[142:145], v[210:213], 0
	v_mfma_f32_16x16x32_bf16 v[72:75], v[160:163], v[210:213], 0
	v_mfma_f32_16x16x32_bf16 v[124:127], v[156:159], v[190:193], v[124:127]
	v_mfma_f32_16x16x32_bf16 v[120:123], v[166:169], v[190:193], v[120:123]
	v_mfma_f32_16x16x32_bf16 v[108:111], v[156:159], v[198:201], v[108:111]
	v_mfma_f32_16x16x32_bf16 v[104:107], v[166:169], v[198:201], v[104:107]
	v_mfma_f32_16x16x32_bf16 v[92:95], v[156:159], v[206:209], v[92:95]
	v_mfma_f32_16x16x32_bf16 v[88:91], v[166:169], v[206:209], v[88:91]
	s_waitcnt lgkmcnt(0)
	v_mfma_f32_16x16x32_bf16 v[76:79], v[156:159], v[214:217], v[76:79]
	v_mfma_f32_16x16x32_bf16 v[72:75], v[166:169], v[214:217], v[72:75]
	s_setprio 0
	s_setprio 1
	v_mfma_f32_16x16x32_bf16 v[116:119], v[170:173], v[186:189], 0
	v_mfma_f32_16x16x32_bf16 v[112:115], v[178:181], v[186:189], 0
	v_mfma_f32_16x16x32_bf16 v[100:103], v[170:173], v[194:197], 0
	v_mfma_f32_16x16x32_bf16 v[96:99], v[178:181], v[194:197], 0
	v_mfma_f32_16x16x32_bf16 v[84:87], v[170:173], v[202:205], 0
	v_mfma_f32_16x16x32_bf16 v[80:83], v[178:181], v[202:205], 0
	v_mfma_f32_16x16x32_bf16 v[68:71], v[170:173], v[210:213], 0
	v_mfma_f32_16x16x32_bf16 v[64:67], v[178:181], v[210:213], 0
	v_mfma_f32_16x16x32_bf16 v[116:119], v[174:177], v[190:193], v[116:119]
	v_mfma_f32_16x16x32_bf16 v[112:115], v[182:185], v[190:193], v[112:115]
	v_mfma_f32_16x16x32_bf16 v[100:103], v[174:177], v[198:201], v[100:103]
	v_mfma_f32_16x16x32_bf16 v[96:99], v[182:185], v[198:201], v[96:99]
	v_mfma_f32_16x16x32_bf16 v[84:87], v[174:177], v[206:209], v[84:87]
	v_mfma_f32_16x16x32_bf16 v[80:83], v[182:185], v[206:209], v[80:83]
	v_mfma_f32_16x16x32_bf16 v[68:71], v[174:177], v[214:217], v[68:71]
	v_mfma_f32_16x16x32_bf16 v[64:67], v[182:185], v[214:217], v[64:67]
	s_setprio 0
	s_barrier
	ds_read_b128 v[186:189], v154 offset:16384
	ds_read_b128 v[190:193], v154 offset:17408
	ds_read_b128 v[194:197], v154 offset:18432
	ds_read_b128 v[198:201], v154 offset:19456
	ds_read_b128 v[202:205], v154 offset:20480
	ds_read_b128 v[206:209], v154 offset:21504
	ds_read_b128 v[210:213], v154 offset:22528
	ds_read_b128 v[214:217], v154 offset:23552
	s_mov_b32 s16, m0
	s_mov_b32 m0, s39
	s_nop 0
	global_load_lds_dwordx4 v146, s[22:23]
	s_mov_b32 m0, s16
	s_nop 0
	s_mov_b32 s16, m0
	s_mov_b32 m0, s40
	s_nop 0
	global_load_lds_dwordx4 v150, s[22:23]
	s_mov_b32 m0, s16
	s_add_u32 s16, s22, 0x100000
	s_addc_u32 s17, s23, 0
	s_mov_b32 s81, m0
	s_mov_b32 m0, s41
	s_nop 0
	global_load_lds_dwordx4 v146, s[16:17]
	s_mov_b32 m0, s81
	s_nop 0
	s_mov_b32 s81, m0
	s_mov_b32 m0, s65
	s_nop 0
	global_load_lds_dwordx4 v150, s[16:17]
	s_mov_b32 m0, s81
	s_mov_b32 s16, m0
	s_mov_b32 m0, s38
	s_nop 0
	global_load_lds_dwordx4 v132, s[24:25]
	s_mov_b32 m0, s16
	s_nop 0
	s_mov_b32 s16, m0
	s_mov_b32 m0, s35
	s_nop 0
	global_load_lds_dwordx4 v147, s[24:25]
	s_mov_b32 m0, s16
	s_waitcnt vmcnt(8)
	s_waitcnt lgkmcnt(0)
	s_barrier
	s_setprio 1
	s_waitcnt lgkmcnt(7)
	v_mfma_f32_16x16x32_bf16 v[60:63], v[142:145], v[186:189], 0
	v_mfma_f32_16x16x32_bf16 v[56:59], v[160:163], v[186:189], 0
	s_waitcnt lgkmcnt(5)
	v_mfma_f32_16x16x32_bf16 v[44:47], v[142:145], v[194:197], 0
	v_mfma_f32_16x16x32_bf16 v[40:43], v[160:163], v[194:197], 0
	s_waitcnt lgkmcnt(3)
	v_mfma_f32_16x16x32_bf16 v[28:31], v[142:145], v[202:205], 0
	v_mfma_f32_16x16x32_bf16 v[24:27], v[160:163], v[202:205], 0
	s_waitcnt lgkmcnt(1)
	v_mfma_f32_16x16x32_bf16 v[12:15], v[142:145], v[210:213], 0
	v_mfma_f32_16x16x32_bf16 v[8:11], v[160:163], v[210:213], 0
	v_mfma_f32_16x16x32_bf16 v[60:63], v[156:159], v[190:193], v[60:63]
	v_mfma_f32_16x16x32_bf16 v[56:59], v[166:169], v[190:193], v[56:59]
	v_mfma_f32_16x16x32_bf16 v[44:47], v[156:159], v[198:201], v[44:47]
	v_mfma_f32_16x16x32_bf16 v[40:43], v[166:169], v[198:201], v[40:43]
	v_mfma_f32_16x16x32_bf16 v[28:31], v[156:159], v[206:209], v[28:31]
	v_mfma_f32_16x16x32_bf16 v[24:27], v[166:169], v[206:209], v[24:27]
	s_waitcnt lgkmcnt(0)
	v_mfma_f32_16x16x32_bf16 v[12:15], v[156:159], v[214:217], v[12:15]
	v_mfma_f32_16x16x32_bf16 v[8:11], v[166:169], v[214:217], v[8:11]
	s_setprio 0
	s_setprio 1
	v_mfma_f32_16x16x32_bf16 v[52:55], v[170:173], v[186:189], 0
	v_mfma_f32_16x16x32_bf16 v[48:51], v[178:181], v[186:189], 0
	v_mfma_f32_16x16x32_bf16 v[36:39], v[170:173], v[194:197], 0
	v_mfma_f32_16x16x32_bf16 v[32:35], v[178:181], v[194:197], 0
	v_mfma_f32_16x16x32_bf16 v[20:23], v[170:173], v[202:205], 0
	v_mfma_f32_16x16x32_bf16 v[16:19], v[178:181], v[202:205], 0
	v_mfma_f32_16x16x32_bf16 v[4:7], v[170:173], v[210:213], 0
	v_mfma_f32_16x16x32_bf16 v[0:3], v[178:181], v[210:213], 0
	v_mfma_f32_16x16x32_bf16 v[52:55], v[174:177], v[190:193], v[52:55]
	v_mfma_f32_16x16x32_bf16 v[48:51], v[182:185], v[190:193], v[48:51]
	v_mfma_f32_16x16x32_bf16 v[36:39], v[174:177], v[198:201], v[36:39]
	v_mfma_f32_16x16x32_bf16 v[32:35], v[182:185], v[198:201], v[32:35]
	v_mfma_f32_16x16x32_bf16 v[20:23], v[174:177], v[206:209], v[20:23]
	v_mfma_f32_16x16x32_bf16 v[16:19], v[182:185], v[206:209], v[16:19]
	v_mfma_f32_16x16x32_bf16 v[4:7], v[174:177], v[214:217], v[4:7]
	v_mfma_f32_16x16x32_bf16 v[0:3], v[182:185], v[214:217], v[0:3]
	s_setprio 0
	s_barrier
	v_add_u32_e32 v155, 0x18000, v153
	ds_read_b128 v[142:145], v155
	ds_read_b128 v[156:159], v155 offset:1024
	ds_read_b128 v[160:163], v155 offset:2048
	ds_read_b128 v[166:169], v155 offset:3072
	v_add_u32_e32 v155, 0x1c000, v153
	ds_read_b128 v[170:173], v155
	ds_read_b128 v[174:177], v155 offset:1024
	ds_read_b128 v[178:181], v155 offset:2048
	ds_read_b128 v[182:185], v155 offset:3072
	ds_read_b128 v[186:189], v154 offset:32768
	ds_read_b128 v[190:193], v154 offset:33792
	ds_read_b128 v[194:197], v154 offset:34816
	ds_read_b128 v[198:201], v154 offset:35840
	ds_read_b128 v[202:205], v154 offset:36864
	ds_read_b128 v[206:209], v154 offset:37888
	ds_read_b128 v[210:213], v154 offset:38912
	ds_read_b128 v[214:217], v154 offset:39936
	s_add_u32 s16, s24, 0x100000
	s_addc_u32 s17, s25, 0
	s_mov_b32 s24, m0
	s_mov_b32 m0, s30
	s_nop 0
	global_load_lds_dwordx4 v132, s[16:17]
	s_mov_b32 m0, s24
	s_nop 0
	s_mov_b32 s24, m0
	s_mov_b32 m0, s31
	s_nop 0
	global_load_lds_dwordx4 v147, s[16:17]
	s_mov_b32 m0, s24
	s_waitcnt vmcnt(8)
	s_waitcnt lgkmcnt(0)
	s_barrier
	s_setprio 1
	s_waitcnt lgkmcnt(7)
	v_mfma_f32_16x16x32_bf16 v[124:127], v[142:145], v[186:189], v[124:127]
	v_mfma_f32_16x16x32_bf16 v[120:123], v[160:163], v[186:189], v[120:123]
	s_waitcnt lgkmcnt(5)
	v_mfma_f32_16x16x32_bf16 v[108:111], v[142:145], v[194:197], v[108:111]
	v_mfma_f32_16x16x32_bf16 v[104:107], v[160:163], v[194:197], v[104:107]
	s_waitcnt lgkmcnt(3)
	v_mfma_f32_16x16x32_bf16 v[92:95], v[142:145], v[202:205], v[92:95]
	v_mfma_f32_16x16x32_bf16 v[88:91], v[160:163], v[202:205], v[88:91]
	s_waitcnt lgkmcnt(1)
	v_mfma_f32_16x16x32_bf16 v[76:79], v[142:145], v[210:213], v[76:79]
	v_mfma_f32_16x16x32_bf16 v[72:75], v[160:163], v[210:213], v[72:75]
	v_mfma_f32_16x16x32_bf16 v[124:127], v[156:159], v[190:193], v[124:127]
	v_mfma_f32_16x16x32_bf16 v[120:123], v[166:169], v[190:193], v[120:123]
	v_mfma_f32_16x16x32_bf16 v[108:111], v[156:159], v[198:201], v[108:111]
	v_mfma_f32_16x16x32_bf16 v[104:107], v[166:169], v[198:201], v[104:107]
	v_mfma_f32_16x16x32_bf16 v[92:95], v[156:159], v[206:209], v[92:95]
	v_mfma_f32_16x16x32_bf16 v[88:91], v[166:169], v[206:209], v[88:91]
	s_waitcnt lgkmcnt(0)
	v_mfma_f32_16x16x32_bf16 v[76:79], v[156:159], v[214:217], v[76:79]
	v_mfma_f32_16x16x32_bf16 v[72:75], v[166:169], v[214:217], v[72:75]
	s_setprio 0
	s_setprio 1
	v_mfma_f32_16x16x32_bf16 v[116:119], v[170:173], v[186:189], v[116:119]
	v_mfma_f32_16x16x32_bf16 v[112:115], v[178:181], v[186:189], v[112:115]
	v_mfma_f32_16x16x32_bf16 v[100:103], v[170:173], v[194:197], v[100:103]
	v_mfma_f32_16x16x32_bf16 v[96:99], v[178:181], v[194:197], v[96:99]
	v_mfma_f32_16x16x32_bf16 v[84:87], v[170:173], v[202:205], v[84:87]
	v_mfma_f32_16x16x32_bf16 v[80:83], v[178:181], v[202:205], v[80:83]
	v_mfma_f32_16x16x32_bf16 v[68:71], v[170:173], v[210:213], v[68:71]
	v_mfma_f32_16x16x32_bf16 v[64:67], v[178:181], v[210:213], v[64:67]
	v_mfma_f32_16x16x32_bf16 v[116:119], v[174:177], v[190:193], v[116:119]
	v_mfma_f32_16x16x32_bf16 v[112:115], v[182:185], v[190:193], v[112:115]
	v_mfma_f32_16x16x32_bf16 v[100:103], v[174:177], v[198:201], v[100:103]
	v_mfma_f32_16x16x32_bf16 v[96:99], v[182:185], v[198:201], v[96:99]
	v_mfma_f32_16x16x32_bf16 v[84:87], v[174:177], v[206:209], v[84:87]
	v_mfma_f32_16x16x32_bf16 v[80:83], v[182:185], v[206:209], v[80:83]
	v_mfma_f32_16x16x32_bf16 v[68:71], v[174:177], v[214:217], v[68:71]
	v_mfma_f32_16x16x32_bf16 v[64:67], v[182:185], v[214:217], v[64:67]
	s_setprio 0
	s_barrier
	ds_read_b128 v[186:189], v154 offset:49152
	ds_read_b128 v[190:193], v154 offset:50176
	ds_read_b128 v[194:197], v154 offset:51200
	ds_read_b128 v[198:201], v154 offset:52224
	ds_read_b128 v[202:205], v154 offset:53248
	ds_read_b128 v[206:209], v154 offset:54272
	ds_read_b128 v[210:213], v154 offset:55296
	ds_read_b128 v[214:217], v154 offset:56320
	s_add_u32 s16, s22, 0x80
	s_addc_u32 s17, s23, 0
	s_mov_b32 s24, m0
	s_mov_b32 m0, s64
	s_nop 0
	global_load_lds_dwordx4 v146, s[16:17]
	s_mov_b32 m0, s24
	s_nop 0
	s_mov_b32 s24, m0
	s_mov_b32 m0, s82
	s_nop 0
	global_load_lds_dwordx4 v150, s[16:17]
	s_mov_b32 m0, s24
	s_add_u32 s16, s22, 0x100080
	s_addc_u32 s17, s23, 0
	s_mov_b32 s22, m0
	s_mov_b32 m0, s66
	s_nop 0
	global_load_lds_dwordx4 v146, s[16:17]
	s_mov_b32 m0, s22
	s_nop 0
	s_mov_b32 s22, m0
	s_mov_b32 m0, s67
	s_nop 0
	global_load_lds_dwordx4 v150, s[16:17]
	s_mov_b32 m0, s22
	s_mov_b32 s16, m0
	s_mov_b32 m0, s44
	s_nop 0
	global_load_lds_dwordx4 v132, s[20:21]
	s_mov_b32 m0, s16
	s_nop 0
	s_mov_b32 s16, m0
	s_mov_b32 m0, s45
	s_nop 0
	global_load_lds_dwordx4 v147, s[20:21]
	s_mov_b32 m0, s16
	s_waitcnt vmcnt(8)
	s_waitcnt lgkmcnt(0)
	s_barrier
	s_setprio 1
	s_waitcnt lgkmcnt(7)
	v_mfma_f32_16x16x32_bf16 v[60:63], v[142:145], v[186:189], v[60:63]
	v_mfma_f32_16x16x32_bf16 v[56:59], v[160:163], v[186:189], v[56:59]
	s_waitcnt lgkmcnt(5)
	v_mfma_f32_16x16x32_bf16 v[44:47], v[142:145], v[194:197], v[44:47]
	v_mfma_f32_16x16x32_bf16 v[40:43], v[160:163], v[194:197], v[40:43]
	s_waitcnt lgkmcnt(3)
	v_mfma_f32_16x16x32_bf16 v[28:31], v[142:145], v[202:205], v[28:31]
	v_mfma_f32_16x16x32_bf16 v[24:27], v[160:163], v[202:205], v[24:27]
	s_waitcnt lgkmcnt(1)
	v_mfma_f32_16x16x32_bf16 v[12:15], v[142:145], v[210:213], v[12:15]
	v_mfma_f32_16x16x32_bf16 v[8:11], v[160:163], v[210:213], v[8:11]
	v_mfma_f32_16x16x32_bf16 v[60:63], v[156:159], v[190:193], v[60:63]
	v_mfma_f32_16x16x32_bf16 v[56:59], v[166:169], v[190:193], v[56:59]
	v_mfma_f32_16x16x32_bf16 v[44:47], v[156:159], v[198:201], v[44:47]
	v_mfma_f32_16x16x32_bf16 v[40:43], v[166:169], v[198:201], v[40:43]
	v_mfma_f32_16x16x32_bf16 v[28:31], v[156:159], v[206:209], v[28:31]
	v_mfma_f32_16x16x32_bf16 v[24:27], v[166:169], v[206:209], v[24:27]
	s_waitcnt lgkmcnt(0)
	v_mfma_f32_16x16x32_bf16 v[12:15], v[156:159], v[214:217], v[12:15]
	v_mfma_f32_16x16x32_bf16 v[8:11], v[166:169], v[214:217], v[8:11]
	s_setprio 0
	s_setprio 1
	v_mfma_f32_16x16x32_bf16 v[52:55], v[170:173], v[186:189], v[52:55]
	v_mfma_f32_16x16x32_bf16 v[48:51], v[178:181], v[186:189], v[48:51]
	v_mfma_f32_16x16x32_bf16 v[36:39], v[170:173], v[194:197], v[36:39]
	v_mfma_f32_16x16x32_bf16 v[32:35], v[178:181], v[194:197], v[32:35]
	v_mfma_f32_16x16x32_bf16 v[20:23], v[170:173], v[202:205], v[20:23]
	v_mfma_f32_16x16x32_bf16 v[16:19], v[178:181], v[202:205], v[16:19]
	v_mfma_f32_16x16x32_bf16 v[4:7], v[170:173], v[210:213], v[4:7]
	v_mfma_f32_16x16x32_bf16 v[0:3], v[178:181], v[210:213], v[0:3]
	v_mfma_f32_16x16x32_bf16 v[52:55], v[174:177], v[190:193], v[52:55]
	v_mfma_f32_16x16x32_bf16 v[48:51], v[182:185], v[190:193], v[48:51]
	v_mfma_f32_16x16x32_bf16 v[36:39], v[174:177], v[198:201], v[36:39]
	v_mfma_f32_16x16x32_bf16 v[32:35], v[182:185], v[198:201], v[32:35]
	v_mfma_f32_16x16x32_bf16 v[20:23], v[174:177], v[206:209], v[20:23]
	v_mfma_f32_16x16x32_bf16 v[16:19], v[182:185], v[206:209], v[16:19]
	v_mfma_f32_16x16x32_bf16 v[4:7], v[174:177], v[214:217], v[4:7]
	v_mfma_f32_16x16x32_bf16 v[0:3], v[182:185], v[214:217], v[0:3]
	s_setprio 0
	s_barrier
	s_add_i32 s80, s80, 2
	s_add_u32 s79, s79, 0x100
	s_addc_u32 vcc_hi, vcc_hi, 0
	s_cmp_gt_u32 s80, 61
	s_mov_b64 s[16:17], s[18:19]
	s_branch .LBB0_733
